# P3 v14: v13 with the two peeled tail steps folded back into the 6-step loop (mid-loop exit), 20% less scan code
# baseline (speedup 1.0000x reference)
.Lp3O_loop:
	ds_read_b128 v[60:63], v241 offset:0
	ds_read_b128 v[12:15], v223 offset:0
	ds_read_b128 v[16:19], v223 offset:4096
	ds_read_b128 v[64:67], v241 offset:4096
	ds_read_b128 v[68:71], v240 offset:0
	ds_read_b128 v[20:23], v222 offset:0
	ds_read_b128 v[24:27], v222 offset:4096
	ds_read_b128 v[72:75], v240 offset:4096
	ds_read_b128 v[76:79], v239 offset:0
	ds_read_b128 v[28:31], v221 offset:0
	ds_read_b128 v[32:35], v221 offset:4096
	ds_read_b128 v[80:83], v239 offset:4096
	s_add_i32 m0, s46, 0x14000
	s_nop 0
	global_load_lds_dwordx4 v255, s[8:9]
	s_add_i32 m0, s46, 0x14400
	s_nop 0
	global_load_lds_dwordx4 v254, s[8:9]
	s_add_i32 m0, s47, 0x14000
	s_nop 0
	global_load_lds_dwordx4 v253, s[10:11]
	s_add_i32 m0, s48, 0x14000
	s_nop 0
	global_load_lds_dwordx4 v252, s[12:13]
	s_add_i32 m0, s48, 0x14400
	s_nop 0
	global_load_lds_dwordx4 v251, s[12:13]
	s_cmp_lt_u32 s33, 29
	s_cselect_b32 s43, 0x10000, 0
	s_add_u32 s8, s8, s43
	s_addc_u32 s9, s9, 0
	s_cmp_lt_u32 s33, 29
	s_cselect_b32 s43, 0x2000, 0
	s_add_u32 s10, s10, s43
	s_addc_u32 s11, s11, 0
	s_cmp_lt_u32 s33, 29
	s_cselect_b32 s43, 0x4000, 0
	s_add_u32 s12, s12, s43
	s_addc_u32 s13, s13, 0
	s_waitcnt lgkmcnt(8)
	v_mfma_f32_16x16x32_bf16 v[108:111], v[12:15], v[60:63], 0
	v_mfma_f32_16x16x32_bf16 v[112:115], v[16:19], v[60:63], 0
	v_mfma_f32_16x16x32_bf16 v[116:119], v[12:15], v[64:67], 0
	v_mfma_f32_16x16x32_bf16 v[120:123], v[16:19], v[64:67], 0
	ds_read_b128 v[84:87], v238 offset:0
	ds_read_b128 v[36:39], v220 offset:0
	ds_read_b128 v[40:43], v220 offset:4096
	ds_read_b128 v[88:91], v238 offset:4096
	s_waitcnt lgkmcnt(8)
	v_mfma_f32_16x16x32_bf16 v[108:111], v[20:23], v[68:71], v[108:111]
	v_mfma_f32_16x16x32_bf16 v[112:115], v[24:27], v[68:71], v[112:115]
	v_mfma_f32_16x16x32_bf16 v[116:119], v[20:23], v[72:75], v[116:119]
	v_mfma_f32_16x16x32_bf16 v[120:123], v[24:27], v[72:75], v[120:123]
	ds_read_b128 v[92:95], v231 offset:0
	ds_read_b128 v[44:47], v219 offset:0
	ds_read_b128 v[48:51], v219 offset:2048
	ds_read_b128 v[96:99], v231 offset:2048
	s_waitcnt lgkmcnt(8)
	v_mfma_f32_16x16x32_bf16 v[108:111], v[28:31], v[76:79], v[108:111]
	v_mfma_f32_16x16x32_bf16 v[112:115], v[32:35], v[76:79], v[112:115]
	v_mfma_f32_16x16x32_bf16 v[116:119], v[28:31], v[80:83], v[116:119]
	v_mfma_f32_16x16x32_bf16 v[120:123], v[32:35], v[80:83], v[120:123]
	ds_read_b128 v[100:103], v230 offset:0
	ds_read_b128 v[52:55], v218 offset:0
	ds_read_b128 v[56:59], v218 offset:2048
	ds_read_b128 v[104:107], v230 offset:2048
	s_waitcnt lgkmcnt(8)
	v_mfma_f32_16x16x32_bf16 v[108:111], v[36:39], v[84:87], v[108:111]
	v_mfma_f32_16x16x32_bf16 v[112:115], v[40:43], v[84:87], v[112:115]
	v_mfma_f32_16x16x32_bf16 v[116:119], v[36:39], v[88:91], v[116:119]
	v_mfma_f32_16x16x32_bf16 v[120:123], v[40:43], v[88:91], v[120:123]
	s_waitcnt lgkmcnt(4)
	v_mfma_f32_16x16x32_bf16 v[108:111], v[44:47], v[92:95], v[108:111]
	v_mfma_f32_16x16x32_bf16 v[112:115], v[48:51], v[92:95], v[112:115]
	v_mfma_f32_16x16x32_bf16 v[116:119], v[44:47], v[96:99], v[116:119]
	v_mfma_f32_16x16x32_bf16 v[120:123], v[48:51], v[96:99], v[120:123]
	s_waitcnt lgkmcnt(0)
	v_mfma_f32_16x16x32_bf16 v[108:111], v[52:55], v[100:103], v[108:111]
	v_mfma_f32_16x16x32_bf16 v[112:115], v[56:59], v[100:103], v[112:115]
	v_mfma_f32_16x16x32_bf16 v[116:119], v[52:55], v[104:107], v[116:119]
	v_mfma_f32_16x16x32_bf16 v[120:123], v[56:59], v[104:107], v[120:123]
	s_nop 7
	s_nop 7
	v_cvt_pk_bf16_f32 v124, v108, v109
	v_cvt_pk_bf16_f32 v125, v110, v111
	v_cvt_pk_bf16_f32 v126, v112, v113
	v_cvt_pk_bf16_f32 v127, v114, v115
	v_cvt_pk_bf16_f32 v128, v116, v117
	v_cvt_pk_bf16_f32 v129, v118, v119
	v_cvt_pk_bf16_f32 v130, v120, v121
	v_cvt_pk_bf16_f32 v131, v122, v123
	global_store_dwordx2 v248, v[124:125], s[18:19]
	global_store_dwordx2 v248, v[126:127], s[18:19] offset:32
	global_store_dwordx2 v247, v[128:129], s[18:19]
	global_store_dwordx2 v247, v[130:131], s[18:19] offset:32
	s_add_u32 s18, s18, 0x20000
	s_addc_u32 s19, s19, 0
	s_add_i32 s33, s33, 1
	s_waitcnt vmcnt(13)
	s_waitcnt lgkmcnt(0)
	s_barrier
	ds_read_b128 v[60:63], v241 offset:40960
	ds_read_b128 v[12:15], v223 offset:12544
	ds_read_b128 v[16:19], v223 offset:16640
	ds_read_b128 v[64:67], v241 offset:45056
	ds_read_b128 v[68:71], v240 offset:40960
	ds_read_b128 v[20:23], v222 offset:12544
	ds_read_b128 v[24:27], v222 offset:16640
	ds_read_b128 v[72:75], v240 offset:45056
	ds_read_b128 v[76:79], v239 offset:40960
	ds_read_b128 v[28:31], v221 offset:12544
	ds_read_b128 v[32:35], v221 offset:16640
	ds_read_b128 v[80:83], v239 offset:45056
	s_mov_b32 m0, s46
	s_nop 0
	global_load_lds_dwordx4 v255, s[8:9]
	s_add_i32 m0, s46, 0x400
	s_nop 0
	global_load_lds_dwordx4 v254, s[8:9]
	s_mov_b32 m0, s47
	s_nop 0
	global_load_lds_dwordx4 v253, s[10:11]
	s_mov_b32 m0, s48
	s_nop 0
	global_load_lds_dwordx4 v252, s[12:13]
	s_add_i32 m0, s48, 0x400
	s_nop 0
	global_load_lds_dwordx4 v251, s[12:13]
	s_cmp_lt_u32 s33, 29
	s_cselect_b32 s43, 0x10000, 0
	s_add_u32 s8, s8, s43
	s_addc_u32 s9, s9, 0
	s_cmp_lt_u32 s33, 29
	s_cselect_b32 s43, 0x2000, 0
	s_add_u32 s10, s10, s43
	s_addc_u32 s11, s11, 0
	s_cmp_lt_u32 s33, 29
	s_cselect_b32 s43, 0x4000, 0
	s_add_u32 s12, s12, s43
	s_addc_u32 s13, s13, 0
	s_waitcnt lgkmcnt(8)
	v_mfma_f32_16x16x32_bf16 v[108:111], v[12:15], v[60:63], 0
	v_mfma_f32_16x16x32_bf16 v[112:115], v[16:19], v[60:63], 0
	v_mfma_f32_16x16x32_bf16 v[116:119], v[12:15], v[64:67], 0
	v_mfma_f32_16x16x32_bf16 v[120:123], v[16:19], v[64:67], 0
	ds_read_b128 v[84:87], v238 offset:40960
	ds_read_b128 v[36:39], v220 offset:12544
	ds_read_b128 v[40:43], v220 offset:16640
	ds_read_b128 v[88:91], v238 offset:45056
	s_waitcnt lgkmcnt(8)
	v_mfma_f32_16x16x32_bf16 v[108:111], v[20:23], v[68:71], v[108:111]
	v_mfma_f32_16x16x32_bf16 v[112:115], v[24:27], v[68:71], v[112:115]
	v_mfma_f32_16x16x32_bf16 v[116:119], v[20:23], v[72:75], v[116:119]
	v_mfma_f32_16x16x32_bf16 v[120:123], v[24:27], v[72:75], v[120:123]
	ds_read_b128 v[92:95], v231 offset:40960
	ds_read_b128 v[44:47], v219 offset:12288
	ds_read_b128 v[48:51], v219 offset:14336
	ds_read_b128 v[96:99], v231 offset:43008
	s_waitcnt lgkmcnt(8)
	v_mfma_f32_16x16x32_bf16 v[108:111], v[28:31], v[76:79], v[108:111]
	v_mfma_f32_16x16x32_bf16 v[112:115], v[32:35], v[76:79], v[112:115]
	v_mfma_f32_16x16x32_bf16 v[116:119], v[28:31], v[80:83], v[116:119]
	v_mfma_f32_16x16x32_bf16 v[120:123], v[32:35], v[80:83], v[120:123]
	ds_read_b128 v[100:103], v230 offset:40960
	ds_read_b128 v[52:55], v218 offset:12288
	ds_read_b128 v[56:59], v218 offset:14336
	ds_read_b128 v[104:107], v230 offset:43008
	s_waitcnt lgkmcnt(8)
	v_mfma_f32_16x16x32_bf16 v[108:111], v[36:39], v[84:87], v[108:111]
	v_mfma_f32_16x16x32_bf16 v[112:115], v[40:43], v[84:87], v[112:115]
	v_mfma_f32_16x16x32_bf16 v[116:119], v[36:39], v[88:91], v[116:119]
	v_mfma_f32_16x16x32_bf16 v[120:123], v[40:43], v[88:91], v[120:123]
	s_waitcnt lgkmcnt(4)
	v_mfma_f32_16x16x32_bf16 v[108:111], v[44:47], v[92:95], v[108:111]
	v_mfma_f32_16x16x32_bf16 v[112:115], v[48:51], v[92:95], v[112:115]
	v_mfma_f32_16x16x32_bf16 v[116:119], v[44:47], v[96:99], v[116:119]
	v_mfma_f32_16x16x32_bf16 v[120:123], v[48:51], v[96:99], v[120:123]
	s_waitcnt lgkmcnt(0)
	v_mfma_f32_16x16x32_bf16 v[108:111], v[52:55], v[100:103], v[108:111]
	v_mfma_f32_16x16x32_bf16 v[112:115], v[56:59], v[100:103], v[112:115]
	v_mfma_f32_16x16x32_bf16 v[116:119], v[52:55], v[104:107], v[116:119]
	v_mfma_f32_16x16x32_bf16 v[120:123], v[56:59], v[104:107], v[120:123]
	s_nop 7
	s_nop 7
	v_cvt_pk_bf16_f32 v124, v108, v109
	v_cvt_pk_bf16_f32 v125, v110, v111
	v_cvt_pk_bf16_f32 v126, v112, v113
	v_cvt_pk_bf16_f32 v127, v114, v115
	v_cvt_pk_bf16_f32 v128, v116, v117
	v_cvt_pk_bf16_f32 v129, v118, v119
	v_cvt_pk_bf16_f32 v130, v120, v121
	v_cvt_pk_bf16_f32 v131, v122, v123
	global_store_dwordx2 v248, v[124:125], s[18:19]
	global_store_dwordx2 v248, v[126:127], s[18:19] offset:32
	global_store_dwordx2 v247, v[128:129], s[18:19]
	global_store_dwordx2 v247, v[130:131], s[18:19] offset:32
	s_add_u32 s18, s18, 0x20000
	s_addc_u32 s19, s19, 0
	s_add_i32 s33, s33, 1
	s_waitcnt vmcnt(13)
	s_waitcnt lgkmcnt(0)
	s_barrier
	s_cmp_gt_u32 s33, 31
	s_cbranch_scc1 .Lp3O_tail
	ds_read_b128 v[60:63], v235 offset:0
	ds_read_b128 v[12:15], v223 offset:0
	ds_read_b128 v[16:19], v223 offset:4096
	ds_read_b128 v[64:67], v235 offset:4096
	ds_read_b128 v[68:71], v234 offset:0
	ds_read_b128 v[20:23], v222 offset:0
	ds_read_b128 v[24:27], v222 offset:4096
	ds_read_b128 v[72:75], v234 offset:4096
	ds_read_b128 v[76:79], v233 offset:0
	ds_read_b128 v[28:31], v221 offset:0
	ds_read_b128 v[32:35], v221 offset:4096
	ds_read_b128 v[80:83], v233 offset:4096
	s_add_i32 m0, s46, 0xa000
	s_nop 0
	global_load_lds_dwordx4 v255, s[8:9]
	s_add_i32 m0, s46, 0xa400
	s_nop 0
	global_load_lds_dwordx4 v254, s[8:9]
	s_add_i32 m0, s47, 0xa000
	s_nop 0
	global_load_lds_dwordx4 v253, s[10:11]
	s_add_i32 m0, s48, 0xa000
	s_nop 0
	global_load_lds_dwordx4 v252, s[12:13]
	s_add_i32 m0, s48, 0xa400
	s_nop 0
	global_load_lds_dwordx4 v251, s[12:13]
	s_cmp_lt_u32 s33, 29
	s_cselect_b32 s43, 0x10000, 0
	s_add_u32 s8, s8, s43
	s_addc_u32 s9, s9, 0
	s_cmp_lt_u32 s33, 29
	s_cselect_b32 s43, 0x2000, 0
	s_add_u32 s10, s10, s43
	s_addc_u32 s11, s11, 0
	s_cmp_lt_u32 s33, 29
	s_cselect_b32 s43, 0x4000, 0
	s_add_u32 s12, s12, s43
	s_addc_u32 s13, s13, 0
	s_waitcnt lgkmcnt(8)
	v_mfma_f32_16x16x32_bf16 v[108:111], v[12:15], v[60:63], 0
	v_mfma_f32_16x16x32_bf16 v[112:115], v[16:19], v[60:63], 0
	v_mfma_f32_16x16x32_bf16 v[116:119], v[12:15], v[64:67], 0
	v_mfma_f32_16x16x32_bf16 v[120:123], v[16:19], v[64:67], 0
	ds_read_b128 v[84:87], v232 offset:0
	ds_read_b128 v[36:39], v220 offset:0
	ds_read_b128 v[40:43], v220 offset:4096
	ds_read_b128 v[88:91], v232 offset:4096
	s_waitcnt lgkmcnt(8)
	v_mfma_f32_16x16x32_bf16 v[108:111], v[20:23], v[68:71], v[108:111]
	v_mfma_f32_16x16x32_bf16 v[112:115], v[24:27], v[68:71], v[112:115]
	v_mfma_f32_16x16x32_bf16 v[116:119], v[20:23], v[72:75], v[116:119]
	v_mfma_f32_16x16x32_bf16 v[120:123], v[24:27], v[72:75], v[120:123]
	ds_read_b128 v[92:95], v229 offset:0
	ds_read_b128 v[44:47], v219 offset:0
	ds_read_b128 v[48:51], v219 offset:2048
	ds_read_b128 v[96:99], v229 offset:2048
	s_waitcnt lgkmcnt(8)
	v_mfma_f32_16x16x32_bf16 v[108:111], v[28:31], v[76:79], v[108:111]
	v_mfma_f32_16x16x32_bf16 v[112:115], v[32:35], v[76:79], v[112:115]
	v_mfma_f32_16x16x32_bf16 v[116:119], v[28:31], v[80:83], v[116:119]
	v_mfma_f32_16x16x32_bf16 v[120:123], v[32:35], v[80:83], v[120:123]
	ds_read_b128 v[100:103], v228 offset:0
	ds_read_b128 v[52:55], v218 offset:0
	ds_read_b128 v[56:59], v218 offset:2048
	ds_read_b128 v[104:107], v228 offset:2048
	s_waitcnt lgkmcnt(8)
	v_mfma_f32_16x16x32_bf16 v[108:111], v[36:39], v[84:87], v[108:111]
	v_mfma_f32_16x16x32_bf16 v[112:115], v[40:43], v[84:87], v[112:115]
	v_mfma_f32_16x16x32_bf16 v[116:119], v[36:39], v[88:91], v[116:119]
	v_mfma_f32_16x16x32_bf16 v[120:123], v[40:43], v[88:91], v[120:123]
	s_waitcnt lgkmcnt(4)
	v_mfma_f32_16x16x32_bf16 v[108:111], v[44:47], v[92:95], v[108:111]
	v_mfma_f32_16x16x32_bf16 v[112:115], v[48:51], v[92:95], v[112:115]
	v_mfma_f32_16x16x32_bf16 v[116:119], v[44:47], v[96:99], v[116:119]
	v_mfma_f32_16x16x32_bf16 v[120:123], v[48:51], v[96:99], v[120:123]
	s_waitcnt lgkmcnt(0)
	v_mfma_f32_16x16x32_bf16 v[108:111], v[52:55], v[100:103], v[108:111]
	v_mfma_f32_16x16x32_bf16 v[112:115], v[56:59], v[100:103], v[112:115]
	v_mfma_f32_16x16x32_bf16 v[116:119], v[52:55], v[104:107], v[116:119]
	v_mfma_f32_16x16x32_bf16 v[120:123], v[56:59], v[104:107], v[120:123]
	s_nop 7
	s_nop 7
	v_cvt_pk_bf16_f32 v124, v108, v109
	v_cvt_pk_bf16_f32 v125, v110, v111
	v_cvt_pk_bf16_f32 v126, v112, v113
	v_cvt_pk_bf16_f32 v127, v114, v115
	v_cvt_pk_bf16_f32 v128, v116, v117
	v_cvt_pk_bf16_f32 v129, v118, v119
	v_cvt_pk_bf16_f32 v130, v120, v121
	v_cvt_pk_bf16_f32 v131, v122, v123
	global_store_dwordx2 v248, v[124:125], s[18:19]
	global_store_dwordx2 v248, v[126:127], s[18:19] offset:32
	global_store_dwordx2 v247, v[128:129], s[18:19]
	global_store_dwordx2 v247, v[130:131], s[18:19] offset:32
	s_add_u32 s18, s18, 0x20000
	s_addc_u32 s19, s19, 0
	s_add_i32 s33, s33, 1
	s_waitcnt vmcnt(13)
	s_waitcnt lgkmcnt(0)
	s_barrier
	ds_read_b128 v[60:63], v241 offset:0
	ds_read_b128 v[12:15], v223 offset:12544
	ds_read_b128 v[16:19], v223 offset:16640
	ds_read_b128 v[64:67], v241 offset:4096
	ds_read_b128 v[68:71], v240 offset:0
	ds_read_b128 v[20:23], v222 offset:12544
	ds_read_b128 v[24:27], v222 offset:16640
	ds_read_b128 v[72:75], v240 offset:4096
	ds_read_b128 v[76:79], v239 offset:0
	ds_read_b128 v[28:31], v221 offset:12544
	ds_read_b128 v[32:35], v221 offset:16640
	ds_read_b128 v[80:83], v239 offset:4096
	s_add_i32 m0, s46, 0x14000
	s_nop 0
	global_load_lds_dwordx4 v255, s[8:9]
	s_add_i32 m0, s46, 0x14400
	s_nop 0
	global_load_lds_dwordx4 v254, s[8:9]
	s_add_i32 m0, s47, 0x14000
	s_nop 0
	global_load_lds_dwordx4 v253, s[10:11]
	s_add_i32 m0, s48, 0x14000
	s_nop 0
	global_load_lds_dwordx4 v252, s[12:13]
	s_add_i32 m0, s48, 0x14400
	s_nop 0
	global_load_lds_dwordx4 v251, s[12:13]
	s_cmp_lt_u32 s33, 29
	s_cselect_b32 s43, 0x10000, 0
	s_add_u32 s8, s8, s43
	s_addc_u32 s9, s9, 0
	s_cmp_lt_u32 s33, 29
	s_cselect_b32 s43, 0x2000, 0
	s_add_u32 s10, s10, s43
	s_addc_u32 s11, s11, 0
	s_cmp_lt_u32 s33, 29
	s_cselect_b32 s43, 0x4000, 0
	s_add_u32 s12, s12, s43
	s_addc_u32 s13, s13, 0
	s_waitcnt lgkmcnt(8)
	v_mfma_f32_16x16x32_bf16 v[108:111], v[12:15], v[60:63], 0
	v_mfma_f32_16x16x32_bf16 v[112:115], v[16:19], v[60:63], 0
	v_mfma_f32_16x16x32_bf16 v[116:119], v[12:15], v[64:67], 0
	v_mfma_f32_16x16x32_bf16 v[120:123], v[16:19], v[64:67], 0
	ds_read_b128 v[84:87], v238 offset:0
	ds_read_b128 v[36:39], v220 offset:12544
	ds_read_b128 v[40:43], v220 offset:16640
	ds_read_b128 v[88:91], v238 offset:4096
	s_waitcnt lgkmcnt(8)
	v_mfma_f32_16x16x32_bf16 v[108:111], v[20:23], v[68:71], v[108:111]
	v_mfma_f32_16x16x32_bf16 v[112:115], v[24:27], v[68:71], v[112:115]
	v_mfma_f32_16x16x32_bf16 v[116:119], v[20:23], v[72:75], v[116:119]
	v_mfma_f32_16x16x32_bf16 v[120:123], v[24:27], v[72:75], v[120:123]
	ds_read_b128 v[92:95], v231 offset:0
	ds_read_b128 v[44:47], v219 offset:12288
	ds_read_b128 v[48:51], v219 offset:14336
	ds_read_b128 v[96:99], v231 offset:2048
	s_waitcnt lgkmcnt(8)
	v_mfma_f32_16x16x32_bf16 v[108:111], v[28:31], v[76:79], v[108:111]
	v_mfma_f32_16x16x32_bf16 v[112:115], v[32:35], v[76:79], v[112:115]
	v_mfma_f32_16x16x32_bf16 v[116:119], v[28:31], v[80:83], v[116:119]
	v_mfma_f32_16x16x32_bf16 v[120:123], v[32:35], v[80:83], v[120:123]
	ds_read_b128 v[100:103], v230 offset:0
	ds_read_b128 v[52:55], v218 offset:12288
	ds_read_b128 v[56:59], v218 offset:14336
	ds_read_b128 v[104:107], v230 offset:2048
	s_waitcnt lgkmcnt(8)
	v_mfma_f32_16x16x32_bf16 v[108:111], v[36:39], v[84:87], v[108:111]
	v_mfma_f32_16x16x32_bf16 v[112:115], v[40:43], v[84:87], v[112:115]
	v_mfma_f32_16x16x32_bf16 v[116:119], v[36:39], v[88:91], v[116:119]
	v_mfma_f32_16x16x32_bf16 v[120:123], v[40:43], v[88:91], v[120:123]
	s_waitcnt lgkmcnt(4)
	v_mfma_f32_16x16x32_bf16 v[108:111], v[44:47], v[92:95], v[108:111]
	v_mfma_f32_16x16x32_bf16 v[112:115], v[48:51], v[92:95], v[112:115]
	v_mfma_f32_16x16x32_bf16 v[116:119], v[44:47], v[96:99], v[116:119]
	v_mfma_f32_16x16x32_bf16 v[120:123], v[48:51], v[96:99], v[120:123]
	s_waitcnt lgkmcnt(0)
	v_mfma_f32_16x16x32_bf16 v[108:111], v[52:55], v[100:103], v[108:111]
	v_mfma_f32_16x16x32_bf16 v[112:115], v[56:59], v[100:103], v[112:115]
	v_mfma_f32_16x16x32_bf16 v[116:119], v[52:55], v[104:107], v[116:119]
	v_mfma_f32_16x16x32_bf16 v[120:123], v[56:59], v[104:107], v[120:123]
	s_nop 7
	s_nop 7
	v_cvt_pk_bf16_f32 v124, v108, v109
	v_cvt_pk_bf16_f32 v125, v110, v111
	v_cvt_pk_bf16_f32 v126, v112, v113
	v_cvt_pk_bf16_f32 v127, v114, v115
	v_cvt_pk_bf16_f32 v128, v116, v117
	v_cvt_pk_bf16_f32 v129, v118, v119
	v_cvt_pk_bf16_f32 v130, v120, v121
	v_cvt_pk_bf16_f32 v131, v122, v123
	global_store_dwordx2 v248, v[124:125], s[18:19]
	global_store_dwordx2 v248, v[126:127], s[18:19] offset:32
	global_store_dwordx2 v247, v[128:129], s[18:19]
	global_store_dwordx2 v247, v[130:131], s[18:19] offset:32
	s_add_u32 s18, s18, 0x20000
	s_addc_u32 s19, s19, 0
	s_add_i32 s33, s33, 1
	s_waitcnt vmcnt(13)
	s_waitcnt lgkmcnt(0)
	s_barrier
	ds_read_b128 v[60:63], v241 offset:40960
	ds_read_b128 v[12:15], v223 offset:0
	ds_read_b128 v[16:19], v223 offset:4096
	ds_read_b128 v[64:67], v241 offset:45056
	ds_read_b128 v[68:71], v240 offset:40960
	ds_read_b128 v[20:23], v222 offset:0
	ds_read_b128 v[24:27], v222 offset:4096
	ds_read_b128 v[72:75], v240 offset:45056
	ds_read_b128 v[76:79], v239 offset:40960
	ds_read_b128 v[28:31], v221 offset:0
	ds_read_b128 v[32:35], v221 offset:4096
	ds_read_b128 v[80:83], v239 offset:45056
	s_mov_b32 m0, s46
	s_nop 0
	global_load_lds_dwordx4 v255, s[8:9]
	s_add_i32 m0, s46, 0x400
	s_nop 0
	global_load_lds_dwordx4 v254, s[8:9]
	s_mov_b32 m0, s47
	s_nop 0
	global_load_lds_dwordx4 v253, s[10:11]
	s_mov_b32 m0, s48
	s_nop 0
	global_load_lds_dwordx4 v252, s[12:13]
	s_add_i32 m0, s48, 0x400
	s_nop 0
	global_load_lds_dwordx4 v251, s[12:13]
	s_cmp_lt_u32 s33, 29
	s_cselect_b32 s43, 0x10000, 0
	s_add_u32 s8, s8, s43
	s_addc_u32 s9, s9, 0
	s_cmp_lt_u32 s33, 29
	s_cselect_b32 s43, 0x2000, 0
	s_add_u32 s10, s10, s43
	s_addc_u32 s11, s11, 0
	s_cmp_lt_u32 s33, 29
	s_cselect_b32 s43, 0x4000, 0
	s_add_u32 s12, s12, s43
	s_addc_u32 s13, s13, 0
	s_waitcnt lgkmcnt(8)
	v_mfma_f32_16x16x32_bf16 v[108:111], v[12:15], v[60:63], 0
	v_mfma_f32_16x16x32_bf16 v[112:115], v[16:19], v[60:63], 0
	v_mfma_f32_16x16x32_bf16 v[116:119], v[12:15], v[64:67], 0
	v_mfma_f32_16x16x32_bf16 v[120:123], v[16:19], v[64:67], 0
	ds_read_b128 v[84:87], v238 offset:40960
	ds_read_b128 v[36:39], v220 offset:0
	ds_read_b128 v[40:43], v220 offset:4096
	ds_read_b128 v[88:91], v238 offset:45056
	s_waitcnt lgkmcnt(8)
; __device__ __forceinline__ void gla_scan_item(const Ctx& C, int item, LAS unsigned char* lds, int tid) {
;     ...
;     for (int n = 0; n < 32; n += 2) { SCAN_STEP(A, n); SCAN_STEP(B, n + 1); }
	v_mfma_f32_16x16x32_bf16 v[108:111], v[20:23], v[68:71], v[108:111]
	v_mfma_f32_16x16x32_bf16 v[112:115], v[24:27], v[68:71], v[112:115]
	v_mfma_f32_16x16x32_bf16 v[116:119], v[20:23], v[72:75], v[116:119]
	v_mfma_f32_16x16x32_bf16 v[120:123], v[24:27], v[72:75], v[120:123]
	ds_read_b128 v[92:95], v231 offset:40960
	ds_read_b128 v[44:47], v219 offset:0
	ds_read_b128 v[48:51], v219 offset:2048
	ds_read_b128 v[96:99], v231 offset:43008
	s_waitcnt lgkmcnt(8)
	v_mfma_f32_16x16x32_bf16 v[108:111], v[28:31], v[76:79], v[108:111]
	v_mfma_f32_16x16x32_bf16 v[112:115], v[32:35], v[76:79], v[112:115]
	v_mfma_f32_16x16x32_bf16 v[116:119], v[28:31], v[80:83], v[116:119]
	v_mfma_f32_16x16x32_bf16 v[120:123], v[32:35], v[80:83], v[120:123]
	ds_read_b128 v[100:103], v230 offset:40960
	ds_read_b128 v[52:55], v218 offset:0
	ds_read_b128 v[56:59], v218 offset:2048
	ds_read_b128 v[104:107], v230 offset:43008
	s_waitcnt lgkmcnt(8)
	v_mfma_f32_16x16x32_bf16 v[108:111], v[36:39], v[84:87], v[108:111]
	v_mfma_f32_16x16x32_bf16 v[112:115], v[40:43], v[84:87], v[112:115]
	v_mfma_f32_16x16x32_bf16 v[116:119], v[36:39], v[88:91], v[116:119]
	v_mfma_f32_16x16x32_bf16 v[120:123], v[40:43], v[88:91], v[120:123]
	s_waitcnt lgkmcnt(4)
	v_mfma_f32_16x16x32_bf16 v[108:111], v[44:47], v[92:95], v[108:111]
	v_mfma_f32_16x16x32_bf16 v[112:115], v[48:51], v[92:95], v[112:115]
	v_mfma_f32_16x16x32_bf16 v[116:119], v[44:47], v[96:99], v[116:119]
	v_mfma_f32_16x16x32_bf16 v[120:123], v[48:51], v[96:99], v[120:123]
	s_waitcnt lgkmcnt(0)
	v_mfma_f32_16x16x32_bf16 v[108:111], v[52:55], v[100:103], v[108:111]
	v_mfma_f32_16x16x32_bf16 v[112:115], v[56:59], v[100:103], v[112:115]
	v_mfma_f32_16x16x32_bf16 v[116:119], v[52:55], v[104:107], v[116:119]
	v_mfma_f32_16x16x32_bf16 v[120:123], v[56:59], v[104:107], v[120:123]
	s_nop 7
	s_nop 7
	v_cvt_pk_bf16_f32 v124, v108, v109
	v_cvt_pk_bf16_f32 v125, v110, v111
	v_cvt_pk_bf16_f32 v126, v112, v113
	v_cvt_pk_bf16_f32 v127, v114, v115
	v_cvt_pk_bf16_f32 v128, v116, v117
	v_cvt_pk_bf16_f32 v129, v118, v119
	v_cvt_pk_bf16_f32 v130, v120, v121
	v_cvt_pk_bf16_f32 v131, v122, v123
	global_store_dwordx2 v248, v[124:125], s[18:19]
	global_store_dwordx2 v248, v[126:127], s[18:19] offset:32
	global_store_dwordx2 v247, v[128:129], s[18:19]
	global_store_dwordx2 v247, v[130:131], s[18:19] offset:32
	s_add_u32 s18, s18, 0x20000
	s_addc_u32 s19, s19, 0
	s_add_i32 s33, s33, 1
	s_waitcnt vmcnt(13)
	s_waitcnt lgkmcnt(0)
	s_barrier
	ds_read_b128 v[60:63], v235 offset:0
	ds_read_b128 v[12:15], v223 offset:12544
	ds_read_b128 v[16:19], v223 offset:16640
	ds_read_b128 v[64:67], v235 offset:4096
	ds_read_b128 v[68:71], v234 offset:0
	ds_read_b128 v[20:23], v222 offset:12544
	ds_read_b128 v[24:27], v222 offset:16640
	ds_read_b128 v[72:75], v234 offset:4096
	ds_read_b128 v[76:79], v233 offset:0
	ds_read_b128 v[28:31], v221 offset:12544
	ds_read_b128 v[32:35], v221 offset:16640
	ds_read_b128 v[80:83], v233 offset:4096
	s_add_i32 m0, s46, 0xa000
	s_nop 0
	global_load_lds_dwordx4 v255, s[8:9]
	s_add_i32 m0, s46, 0xa400
	s_nop 0
	global_load_lds_dwordx4 v254, s[8:9]
	s_add_i32 m0, s47, 0xa000
	s_nop 0
	global_load_lds_dwordx4 v253, s[10:11]
	s_add_i32 m0, s48, 0xa000
	s_nop 0
	global_load_lds_dwordx4 v252, s[12:13]
	s_add_i32 m0, s48, 0xa400
	s_nop 0
	global_load_lds_dwordx4 v251, s[12:13]
	s_cmp_lt_u32 s33, 29
	s_cselect_b32 s43, 0x10000, 0
	s_add_u32 s8, s8, s43
	s_addc_u32 s9, s9, 0
	s_cmp_lt_u32 s33, 29
	s_cselect_b32 s43, 0x2000, 0
	s_add_u32 s10, s10, s43
	s_addc_u32 s11, s11, 0
	s_cmp_lt_u32 s33, 29
	s_cselect_b32 s43, 0x4000, 0
	s_add_u32 s12, s12, s43
	s_addc_u32 s13, s13, 0
	s_waitcnt lgkmcnt(8)
	v_mfma_f32_16x16x32_bf16 v[108:111], v[12:15], v[60:63], 0
	v_mfma_f32_16x16x32_bf16 v[112:115], v[16:19], v[60:63], 0
	v_mfma_f32_16x16x32_bf16 v[116:119], v[12:15], v[64:67], 0
	v_mfma_f32_16x16x32_bf16 v[120:123], v[16:19], v[64:67], 0
	ds_read_b128 v[84:87], v232 offset:0
	ds_read_b128 v[36:39], v220 offset:12544
	ds_read_b128 v[40:43], v220 offset:16640
	ds_read_b128 v[88:91], v232 offset:4096
	s_waitcnt lgkmcnt(8)
	v_mfma_f32_16x16x32_bf16 v[108:111], v[20:23], v[68:71], v[108:111]
	v_mfma_f32_16x16x32_bf16 v[112:115], v[24:27], v[68:71], v[112:115]
	v_mfma_f32_16x16x32_bf16 v[116:119], v[20:23], v[72:75], v[116:119]
	v_mfma_f32_16x16x32_bf16 v[120:123], v[24:27], v[72:75], v[120:123]
	ds_read_b128 v[92:95], v229 offset:0
	ds_read_b128 v[44:47], v219 offset:12288
	ds_read_b128 v[48:51], v219 offset:14336
	ds_read_b128 v[96:99], v229 offset:2048
	s_waitcnt lgkmcnt(8)
	v_mfma_f32_16x16x32_bf16 v[108:111], v[28:31], v[76:79], v[108:111]
	v_mfma_f32_16x16x32_bf16 v[112:115], v[32:35], v[76:79], v[112:115]
	v_mfma_f32_16x16x32_bf16 v[116:119], v[28:31], v[80:83], v[116:119]
	v_mfma_f32_16x16x32_bf16 v[120:123], v[32:35], v[80:83], v[120:123]
	ds_read_b128 v[100:103], v228 offset:0
	ds_read_b128 v[52:55], v218 offset:12288
	ds_read_b128 v[56:59], v218 offset:14336
	ds_read_b128 v[104:107], v228 offset:2048
	s_waitcnt lgkmcnt(8)
	v_mfma_f32_16x16x32_bf16 v[108:111], v[36:39], v[84:87], v[108:111]
	v_mfma_f32_16x16x32_bf16 v[112:115], v[40:43], v[84:87], v[112:115]
	v_mfma_f32_16x16x32_bf16 v[116:119], v[36:39], v[88:91], v[116:119]
	v_mfma_f32_16x16x32_bf16 v[120:123], v[40:43], v[88:91], v[120:123]
	s_waitcnt lgkmcnt(4)
	v_mfma_f32_16x16x32_bf16 v[108:111], v[44:47], v[92:95], v[108:111]
	v_mfma_f32_16x16x32_bf16 v[112:115], v[48:51], v[92:95], v[112:115]
	v_mfma_f32_16x16x32_bf16 v[116:119], v[44:47], v[96:99], v[116:119]
	v_mfma_f32_16x16x32_bf16 v[120:123], v[48:51], v[96:99], v[120:123]
	s_waitcnt lgkmcnt(0)
	v_mfma_f32_16x16x32_bf16 v[108:111], v[52:55], v[100:103], v[108:111]
	v_mfma_f32_16x16x32_bf16 v[112:115], v[56:59], v[100:103], v[112:115]
	v_mfma_f32_16x16x32_bf16 v[116:119], v[52:55], v[104:107], v[116:119]
	v_mfma_f32_16x16x32_bf16 v[120:123], v[56:59], v[104:107], v[120:123]
	s_nop 7
	s_nop 7
	v_cvt_pk_bf16_f32 v124, v108, v109
	v_cvt_pk_bf16_f32 v125, v110, v111
	v_cvt_pk_bf16_f32 v126, v112, v113
	v_cvt_pk_bf16_f32 v127, v114, v115
	v_cvt_pk_bf16_f32 v128, v116, v117
	v_cvt_pk_bf16_f32 v129, v118, v119
	v_cvt_pk_bf16_f32 v130, v120, v121
	v_cvt_pk_bf16_f32 v131, v122, v123
	global_store_dwordx2 v248, v[124:125], s[18:19]
	global_store_dwordx2 v248, v[126:127], s[18:19] offset:32
	global_store_dwordx2 v247, v[128:129], s[18:19]
	global_store_dwordx2 v247, v[130:131], s[18:19] offset:32
	s_add_u32 s18, s18, 0x20000
	s_addc_u32 s19, s19, 0
	s_add_i32 s33, s33, 1
	s_waitcnt vmcnt(13)
	s_waitcnt lgkmcnt(0)
	s_barrier
	s_branch .Lp3O_loop
.Lp3O_tail:
	s_waitcnt vmcnt(0) lgkmcnt(0)
	s_barrier
	s_add_i32 s3, s3, s42
	s_cmpk_lt_i32 s3, 0x100
	s_cbranch_scc1 .Lp3O_item
	s_branch .Lp3_done

.Lp3S_loop:
	ds_read_b128 v[44:47], v217 offset:0
	ds_read_b128 v[48:51], v217 offset:2048
	ds_read_b128 v[12:15], v227 offset:0
	ds_read_b128 v[16:19], v227 offset:2048
	ds_read_b128 v[20:23], v227 offset:4096
	ds_read_b128 v[24:27], v227 offset:6144
	ds_read_b128 v[52:55], v216 offset:0
	ds_read_b128 v[56:59], v216 offset:2048
	ds_read_b128 v[28:31], v226 offset:0
	ds_read_b128 v[32:35], v226 offset:2048
	ds_read_b128 v[36:39], v226 offset:4096
	ds_read_b128 v[40:43], v226 offset:6144
	s_waitcnt vmcnt(12)
	v_mov_b32_dpp v96, v92 quad_perm:[0,0,0,0] row_mask:0xf bank_mask:0xf
	v_mov_b32_dpp v97, v93 quad_perm:[0,0,0,0] row_mask:0xf bank_mask:0xf
	v_mov_b32_dpp v98, v94 quad_perm:[0,0,0,0] row_mask:0xf bank_mask:0xf
	v_mov_b32_dpp v99, v95 quad_perm:[0,0,0,0] row_mask:0xf bank_mask:0xf
	v_mov_b32_dpp v100, v92 quad_perm:[1,1,1,1] row_mask:0xf bank_mask:0xf
	v_mov_b32_dpp v101, v93 quad_perm:[1,1,1,1] row_mask:0xf bank_mask:0xf
	v_mov_b32_dpp v102, v94 quad_perm:[1,1,1,1] row_mask:0xf bank_mask:0xf
	v_mov_b32_dpp v103, v95 quad_perm:[1,1,1,1] row_mask:0xf bank_mask:0xf
	v_mov_b32_dpp v104, v92 quad_perm:[2,2,2,2] row_mask:0xf bank_mask:0xf
	v_mov_b32_dpp v105, v93 quad_perm:[2,2,2,2] row_mask:0xf bank_mask:0xf
	v_mov_b32_dpp v106, v94 quad_perm:[2,2,2,2] row_mask:0xf bank_mask:0xf
	v_mov_b32_dpp v107, v95 quad_perm:[2,2,2,2] row_mask:0xf bank_mask:0xf
	v_mov_b32_dpp v112, v92 quad_perm:[3,3,3,3] row_mask:0xf bank_mask:0xf
	v_mov_b32_dpp v113, v93 quad_perm:[3,3,3,3] row_mask:0xf bank_mask:0xf
	v_mov_b32_dpp v114, v94 quad_perm:[3,3,3,3] row_mask:0xf bank_mask:0xf
	v_mov_b32_dpp v115, v95 quad_perm:[3,3,3,3] row_mask:0xf bank_mask:0xf
	v_pk_mul_f32 v[60:61], v[60:61], v[96:97]
	v_pk_mul_f32 v[62:63], v[62:63], v[98:99]
	v_pk_mul_f32 v[64:65], v[64:65], v[96:97]
	v_pk_mul_f32 v[66:67], v[66:67], v[98:99]
	v_pk_mul_f32 v[68:69], v[68:69], v[100:101]
	v_pk_mul_f32 v[70:71], v[70:71], v[102:103]
	v_pk_mul_f32 v[72:73], v[72:73], v[100:101]
	v_pk_mul_f32 v[74:75], v[74:75], v[102:103]
	v_pk_mul_f32 v[76:77], v[76:77], v[104:105]
	v_pk_mul_f32 v[78:79], v[78:79], v[106:107]
	v_pk_mul_f32 v[80:81], v[80:81], v[104:105]
	v_pk_mul_f32 v[82:83], v[82:83], v[106:107]
	v_pk_mul_f32 v[84:85], v[84:85], v[112:113]
	v_pk_mul_f32 v[86:87], v[86:87], v[114:115]
	v_pk_mul_f32 v[88:89], v[88:89], v[112:113]
	v_pk_mul_f32 v[90:91], v[90:91], v[114:115]
	s_add_i32 m0, s46, 0x14000
	s_nop 0
	global_load_lds_dwordx4 v255, s[8:9]
	s_add_i32 m0, s46, 0x14400
	s_nop 0
	global_load_lds_dwordx4 v254, s[8:9]
	s_add_i32 m0, s47, 0x14000
	s_nop 0
	global_load_lds_dwordx4 v253, s[10:11]
	s_add_i32 m0, s48, 0x14000
	s_nop 0
	global_load_lds_dwordx4 v252, s[12:13]
	s_add_i32 m0, s48, 0x14400
	s_nop 0
	global_load_lds_dwordx4 v251, s[12:13]
	s_cmp_lt_u32 s33, 29
	s_cselect_b32 s43, 0x10000, 0
	s_add_u32 s8, s8, s43
	s_addc_u32 s9, s9, 0
	s_cmp_lt_u32 s33, 29
	s_cselect_b32 s43, 0x2000, 0
	s_add_u32 s10, s10, s43
	s_addc_u32 s11, s11, 0
	s_cmp_lt_u32 s33, 29
	s_cselect_b32 s43, 0x4000, 0
	s_add_u32 s12, s12, s43
	s_addc_u32 s13, s13, 0
	s_waitcnt lgkmcnt(6)
	v_mfma_f32_16x16x32_bf16 v[60:63], v[12:15], v[44:47], v[60:63]
	v_mfma_f32_16x16x32_bf16 v[64:67], v[12:15], v[48:51], v[64:67]
	v_mfma_f32_16x16x32_bf16 v[68:71], v[16:19], v[44:47], v[68:71]
	v_mfma_f32_16x16x32_bf16 v[72:75], v[16:19], v[48:51], v[72:75]
	v_mfma_f32_16x16x32_bf16 v[76:79], v[20:23], v[44:47], v[76:79]
	v_mfma_f32_16x16x32_bf16 v[80:83], v[20:23], v[48:51], v[80:83]
	v_mfma_f32_16x16x32_bf16 v[84:87], v[24:27], v[44:47], v[84:87]
	v_mfma_f32_16x16x32_bf16 v[88:91], v[24:27], v[48:51], v[88:91]
	s_waitcnt lgkmcnt(0)
	v_mfma_f32_16x16x32_bf16 v[60:63], v[28:31], v[52:55], v[60:63]
	v_mfma_f32_16x16x32_bf16 v[64:67], v[28:31], v[56:59], v[64:67]
	v_mfma_f32_16x16x32_bf16 v[68:71], v[32:35], v[52:55], v[68:71]
	v_mfma_f32_16x16x32_bf16 v[72:75], v[32:35], v[56:59], v[72:75]
	v_mfma_f32_16x16x32_bf16 v[76:79], v[36:39], v[52:55], v[76:79]
	v_mfma_f32_16x16x32_bf16 v[80:83], v[36:39], v[56:59], v[80:83]
	v_mfma_f32_16x16x32_bf16 v[84:87], v[40:43], v[52:55], v[84:87]
	v_mfma_f32_16x16x32_bf16 v[88:91], v[40:43], v[56:59], v[88:91]
	s_nop 3
	global_load_dwordx4 v[92:95], v249, s[16:17]
	s_cmp_lt_u32 s33, 28
	s_cselect_b32 s43, 0x200, 0
	s_add_u32 s16, s16, s43
	s_addc_u32 s17, s17, 0
	s_add_i32 s33, s33, 1
	s_nop 7
	s_nop 7
	v_cvt_pk_bf16_f32 v140, v60, v61
	v_cvt_pk_bf16_f32 v141, v62, v63
	ds_write_b64 v215, v[140:141] offset:12544
	v_cvt_pk_bf16_f32 v144, v64, v65
	v_cvt_pk_bf16_f32 v145, v66, v67
	ds_write_b64 v215, v[144:145] offset:16640
	s_nop 1
	v_cvt_pk_bf16_f32 v140, v68, v69
	v_cvt_pk_bf16_f32 v141, v70, v71
	ds_write_b64 v214, v[140:141] offset:12544
	v_cvt_pk_bf16_f32 v144, v72, v73
	v_cvt_pk_bf16_f32 v145, v74, v75
	ds_write_b64 v214, v[144:145] offset:16640
	s_nop 1
	v_cvt_pk_bf16_f32 v140, v76, v77
	v_cvt_pk_bf16_f32 v141, v78, v79
	ds_write_b64 v213, v[140:141] offset:12544
	v_cvt_pk_bf16_f32 v144, v80, v81
	v_cvt_pk_bf16_f32 v145, v82, v83
	ds_write_b64 v213, v[144:145] offset:16640
	s_nop 1
	v_cvt_pk_bf16_f32 v140, v84, v85
	v_cvt_pk_bf16_f32 v141, v86, v87
	ds_write_b64 v212, v[140:141] offset:12544
	v_cvt_pk_bf16_f32 v144, v88, v89
	v_cvt_pk_bf16_f32 v145, v90, v91
	ds_write_b64 v212, v[144:145] offset:16640
	s_nop 1
	s_waitcnt vmcnt(7)
	s_waitcnt lgkmcnt(0)
	s_barrier
	ds_read_b128 v[44:47], v217 offset:12288
	ds_read_b128 v[48:51], v217 offset:14336
	ds_read_b128 v[12:15], v227 offset:40960
	ds_read_b128 v[16:19], v227 offset:43008
	ds_read_b128 v[20:23], v227 offset:45056
	ds_read_b128 v[24:27], v227 offset:47104
	ds_read_b128 v[52:55], v216 offset:12288
	ds_read_b128 v[56:59], v216 offset:14336
	ds_read_b128 v[28:31], v226 offset:40960
	ds_read_b128 v[32:35], v226 offset:43008
	ds_read_b128 v[36:39], v226 offset:45056
	ds_read_b128 v[40:43], v226 offset:47104
	s_waitcnt vmcnt(12)
	v_mov_b32_dpp v96, v108 quad_perm:[0,0,0,0] row_mask:0xf bank_mask:0xf
	v_mov_b32_dpp v97, v109 quad_perm:[0,0,0,0] row_mask:0xf bank_mask:0xf
	v_mov_b32_dpp v98, v110 quad_perm:[0,0,0,0] row_mask:0xf bank_mask:0xf
	v_mov_b32_dpp v99, v111 quad_perm:[0,0,0,0] row_mask:0xf bank_mask:0xf
	v_mov_b32_dpp v100, v108 quad_perm:[1,1,1,1] row_mask:0xf bank_mask:0xf
	v_mov_b32_dpp v101, v109 quad_perm:[1,1,1,1] row_mask:0xf bank_mask:0xf
	v_mov_b32_dpp v102, v110 quad_perm:[1,1,1,1] row_mask:0xf bank_mask:0xf
	v_mov_b32_dpp v103, v111 quad_perm:[1,1,1,1] row_mask:0xf bank_mask:0xf
	v_mov_b32_dpp v104, v108 quad_perm:[2,2,2,2] row_mask:0xf bank_mask:0xf
	v_mov_b32_dpp v105, v109 quad_perm:[2,2,2,2] row_mask:0xf bank_mask:0xf
	v_mov_b32_dpp v106, v110 quad_perm:[2,2,2,2] row_mask:0xf bank_mask:0xf
	v_mov_b32_dpp v107, v111 quad_perm:[2,2,2,2] row_mask:0xf bank_mask:0xf
	v_mov_b32_dpp v112, v108 quad_perm:[3,3,3,3] row_mask:0xf bank_mask:0xf
	v_mov_b32_dpp v113, v109 quad_perm:[3,3,3,3] row_mask:0xf bank_mask:0xf
	v_mov_b32_dpp v114, v110 quad_perm:[3,3,3,3] row_mask:0xf bank_mask:0xf
	v_mov_b32_dpp v115, v111 quad_perm:[3,3,3,3] row_mask:0xf bank_mask:0xf
	v_pk_mul_f32 v[60:61], v[60:61], v[96:97]
	v_pk_mul_f32 v[62:63], v[62:63], v[98:99]
	v_pk_mul_f32 v[64:65], v[64:65], v[96:97]
	v_pk_mul_f32 v[66:67], v[66:67], v[98:99]
	v_pk_mul_f32 v[68:69], v[68:69], v[100:101]
	v_pk_mul_f32 v[70:71], v[70:71], v[102:103]
	v_pk_mul_f32 v[72:73], v[72:73], v[100:101]
	v_pk_mul_f32 v[74:75], v[74:75], v[102:103]
	v_pk_mul_f32 v[76:77], v[76:77], v[104:105]
	v_pk_mul_f32 v[78:79], v[78:79], v[106:107]
	v_pk_mul_f32 v[80:81], v[80:81], v[104:105]
	v_pk_mul_f32 v[82:83], v[82:83], v[106:107]
	v_pk_mul_f32 v[84:85], v[84:85], v[112:113]
	v_pk_mul_f32 v[86:87], v[86:87], v[114:115]
	v_pk_mul_f32 v[88:89], v[88:89], v[112:113]
	v_pk_mul_f32 v[90:91], v[90:91], v[114:115]
	s_mov_b32 m0, s46
	s_nop 0
	global_load_lds_dwordx4 v255, s[8:9]
	s_add_i32 m0, s46, 0x400
	s_nop 0
	global_load_lds_dwordx4 v254, s[8:9]
	s_mov_b32 m0, s47
	s_nop 0
	global_load_lds_dwordx4 v253, s[10:11]
	s_mov_b32 m0, s48
	s_nop 0
	global_load_lds_dwordx4 v252, s[12:13]
	s_add_i32 m0, s48, 0x400
	s_nop 0
	global_load_lds_dwordx4 v251, s[12:13]
	s_cmp_lt_u32 s33, 29
	s_cselect_b32 s43, 0x10000, 0
	s_add_u32 s8, s8, s43
	s_addc_u32 s9, s9, 0
	s_cmp_lt_u32 s33, 29
	s_cselect_b32 s43, 0x2000, 0
	s_add_u32 s10, s10, s43
	s_addc_u32 s11, s11, 0
	s_cmp_lt_u32 s33, 29
	s_cselect_b32 s43, 0x4000, 0
	s_add_u32 s12, s12, s43
	s_addc_u32 s13, s13, 0
	s_waitcnt lgkmcnt(6)
	v_mfma_f32_16x16x32_bf16 v[60:63], v[12:15], v[44:47], v[60:63]
	v_mfma_f32_16x16x32_bf16 v[64:67], v[12:15], v[48:51], v[64:67]
	v_mfma_f32_16x16x32_bf16 v[68:71], v[16:19], v[44:47], v[68:71]
	v_mfma_f32_16x16x32_bf16 v[72:75], v[16:19], v[48:51], v[72:75]
	v_mfma_f32_16x16x32_bf16 v[76:79], v[20:23], v[44:47], v[76:79]
	v_mfma_f32_16x16x32_bf16 v[80:83], v[20:23], v[48:51], v[80:83]
	v_mfma_f32_16x16x32_bf16 v[84:87], v[24:27], v[44:47], v[84:87]
	v_mfma_f32_16x16x32_bf16 v[88:91], v[24:27], v[48:51], v[88:91]
	s_waitcnt lgkmcnt(0)
	v_mfma_f32_16x16x32_bf16 v[60:63], v[28:31], v[52:55], v[60:63]
	v_mfma_f32_16x16x32_bf16 v[64:67], v[28:31], v[56:59], v[64:67]
	v_mfma_f32_16x16x32_bf16 v[68:71], v[32:35], v[52:55], v[68:71]
	v_mfma_f32_16x16x32_bf16 v[72:75], v[32:35], v[56:59], v[72:75]
	v_mfma_f32_16x16x32_bf16 v[76:79], v[36:39], v[52:55], v[76:79]
	v_mfma_f32_16x16x32_bf16 v[80:83], v[36:39], v[56:59], v[80:83]
	v_mfma_f32_16x16x32_bf16 v[84:87], v[40:43], v[52:55], v[84:87]
	v_mfma_f32_16x16x32_bf16 v[88:91], v[40:43], v[56:59], v[88:91]
	s_nop 3
	global_load_dwordx4 v[108:111], v249, s[16:17]
	s_cmp_lt_u32 s33, 28
	s_cselect_b32 s43, 0x200, 0
	s_add_u32 s16, s16, s43
	s_addc_u32 s17, s17, 0
	s_add_i32 s33, s33, 1
	s_nop 7
	s_nop 7
	v_cvt_pk_bf16_f32 v140, v60, v61
	v_cvt_pk_bf16_f32 v141, v62, v63
	ds_write_b64 v215, v[140:141] offset:0
	v_cvt_pk_bf16_f32 v144, v64, v65
	v_cvt_pk_bf16_f32 v145, v66, v67
	ds_write_b64 v215, v[144:145] offset:4096
	s_nop 1
	v_cvt_pk_bf16_f32 v140, v68, v69
	v_cvt_pk_bf16_f32 v141, v70, v71
	ds_write_b64 v214, v[140:141] offset:0
	v_cvt_pk_bf16_f32 v144, v72, v73
	v_cvt_pk_bf16_f32 v145, v74, v75
	ds_write_b64 v214, v[144:145] offset:4096
	s_nop 1
	v_cvt_pk_bf16_f32 v140, v76, v77
	v_cvt_pk_bf16_f32 v141, v78, v79
	ds_write_b64 v213, v[140:141] offset:0
	v_cvt_pk_bf16_f32 v144, v80, v81
	v_cvt_pk_bf16_f32 v145, v82, v83
	ds_write_b64 v213, v[144:145] offset:4096
	s_nop 1
	v_cvt_pk_bf16_f32 v140, v84, v85
	v_cvt_pk_bf16_f32 v141, v86, v87
	ds_write_b64 v212, v[140:141] offset:0
	v_cvt_pk_bf16_f32 v144, v88, v89
	v_cvt_pk_bf16_f32 v145, v90, v91
	ds_write_b64 v212, v[144:145] offset:4096
	s_nop 1
	s_waitcnt vmcnt(7)
	s_waitcnt lgkmcnt(0)
	s_barrier
	s_cmp_gt_u32 s33, 31
	s_cbranch_scc1 .Lp3S_tail
	ds_read_b128 v[44:47], v217 offset:0
	ds_read_b128 v[48:51], v217 offset:2048
	ds_read_b128 v[12:15], v225 offset:0
	ds_read_b128 v[16:19], v225 offset:2048
	ds_read_b128 v[20:23], v225 offset:4096
	ds_read_b128 v[24:27], v225 offset:6144
	ds_read_b128 v[52:55], v216 offset:0
	ds_read_b128 v[56:59], v216 offset:2048
	ds_read_b128 v[28:31], v224 offset:0
	ds_read_b128 v[32:35], v224 offset:2048
	ds_read_b128 v[36:39], v224 offset:4096
	ds_read_b128 v[40:43], v224 offset:6144
	s_waitcnt vmcnt(12)
	v_mov_b32_dpp v96, v124 quad_perm:[0,0,0,0] row_mask:0xf bank_mask:0xf
	v_mov_b32_dpp v97, v125 quad_perm:[0,0,0,0] row_mask:0xf bank_mask:0xf
	v_mov_b32_dpp v98, v126 quad_perm:[0,0,0,0] row_mask:0xf bank_mask:0xf
	v_mov_b32_dpp v99, v127 quad_perm:[0,0,0,0] row_mask:0xf bank_mask:0xf
	v_mov_b32_dpp v100, v124 quad_perm:[1,1,1,1] row_mask:0xf bank_mask:0xf
	v_mov_b32_dpp v101, v125 quad_perm:[1,1,1,1] row_mask:0xf bank_mask:0xf
	v_mov_b32_dpp v102, v126 quad_perm:[1,1,1,1] row_mask:0xf bank_mask:0xf
	v_mov_b32_dpp v103, v127 quad_perm:[1,1,1,1] row_mask:0xf bank_mask:0xf
	v_mov_b32_dpp v104, v124 quad_perm:[2,2,2,2] row_mask:0xf bank_mask:0xf
	v_mov_b32_dpp v105, v125 quad_perm:[2,2,2,2] row_mask:0xf bank_mask:0xf
	v_mov_b32_dpp v106, v126 quad_perm:[2,2,2,2] row_mask:0xf bank_mask:0xf
	v_mov_b32_dpp v107, v127 quad_perm:[2,2,2,2] row_mask:0xf bank_mask:0xf
	v_mov_b32_dpp v112, v124 quad_perm:[3,3,3,3] row_mask:0xf bank_mask:0xf
	v_mov_b32_dpp v113, v125 quad_perm:[3,3,3,3] row_mask:0xf bank_mask:0xf
	v_mov_b32_dpp v114, v126 quad_perm:[3,3,3,3] row_mask:0xf bank_mask:0xf
	v_mov_b32_dpp v115, v127 quad_perm:[3,3,3,3] row_mask:0xf bank_mask:0xf
	v_pk_mul_f32 v[60:61], v[60:61], v[96:97]
	v_pk_mul_f32 v[62:63], v[62:63], v[98:99]
	v_pk_mul_f32 v[64:65], v[64:65], v[96:97]
	v_pk_mul_f32 v[66:67], v[66:67], v[98:99]
	v_pk_mul_f32 v[68:69], v[68:69], v[100:101]
	v_pk_mul_f32 v[70:71], v[70:71], v[102:103]
	v_pk_mul_f32 v[72:73], v[72:73], v[100:101]
	v_pk_mul_f32 v[74:75], v[74:75], v[102:103]
	v_pk_mul_f32 v[76:77], v[76:77], v[104:105]
	v_pk_mul_f32 v[78:79], v[78:79], v[106:107]
	v_pk_mul_f32 v[80:81], v[80:81], v[104:105]
	v_pk_mul_f32 v[82:83], v[82:83], v[106:107]
	v_pk_mul_f32 v[84:85], v[84:85], v[112:113]
	v_pk_mul_f32 v[86:87], v[86:87], v[114:115]
	v_pk_mul_f32 v[88:89], v[88:89], v[112:113]
	v_pk_mul_f32 v[90:91], v[90:91], v[114:115]
	s_add_i32 m0, s46, 0xa000
	s_nop 0
	global_load_lds_dwordx4 v255, s[8:9]
	s_add_i32 m0, s46, 0xa400
	s_nop 0
	global_load_lds_dwordx4 v254, s[8:9]
	s_add_i32 m0, s47, 0xa000
	s_nop 0
	global_load_lds_dwordx4 v253, s[10:11]
	s_add_i32 m0, s48, 0xa000
	s_nop 0
	global_load_lds_dwordx4 v252, s[12:13]
	s_add_i32 m0, s48, 0xa400
	s_nop 0
	global_load_lds_dwordx4 v251, s[12:13]
	s_cmp_lt_u32 s33, 29
	s_cselect_b32 s43, 0x10000, 0
	s_add_u32 s8, s8, s43
	s_addc_u32 s9, s9, 0
	s_cmp_lt_u32 s33, 29
	s_cselect_b32 s43, 0x2000, 0
	s_add_u32 s10, s10, s43
	s_addc_u32 s11, s11, 0
	s_cmp_lt_u32 s33, 29
	s_cselect_b32 s43, 0x4000, 0
	s_add_u32 s12, s12, s43
	s_addc_u32 s13, s13, 0
	s_waitcnt lgkmcnt(6)
	v_mfma_f32_16x16x32_bf16 v[60:63], v[12:15], v[44:47], v[60:63]
	v_mfma_f32_16x16x32_bf16 v[64:67], v[12:15], v[48:51], v[64:67]
	v_mfma_f32_16x16x32_bf16 v[68:71], v[16:19], v[44:47], v[68:71]
	v_mfma_f32_16x16x32_bf16 v[72:75], v[16:19], v[48:51], v[72:75]
	v_mfma_f32_16x16x32_bf16 v[76:79], v[20:23], v[44:47], v[76:79]
	v_mfma_f32_16x16x32_bf16 v[80:83], v[20:23], v[48:51], v[80:83]
	v_mfma_f32_16x16x32_bf16 v[84:87], v[24:27], v[44:47], v[84:87]
	v_mfma_f32_16x16x32_bf16 v[88:91], v[24:27], v[48:51], v[88:91]
	s_waitcnt lgkmcnt(0)
	v_mfma_f32_16x16x32_bf16 v[60:63], v[28:31], v[52:55], v[60:63]
	v_mfma_f32_16x16x32_bf16 v[64:67], v[28:31], v[56:59], v[64:67]
	v_mfma_f32_16x16x32_bf16 v[68:71], v[32:35], v[52:55], v[68:71]
	v_mfma_f32_16x16x32_bf16 v[72:75], v[32:35], v[56:59], v[72:75]
	v_mfma_f32_16x16x32_bf16 v[76:79], v[36:39], v[52:55], v[76:79]
	v_mfma_f32_16x16x32_bf16 v[80:83], v[36:39], v[56:59], v[80:83]
	v_mfma_f32_16x16x32_bf16 v[84:87], v[40:43], v[52:55], v[84:87]
	v_mfma_f32_16x16x32_bf16 v[88:91], v[40:43], v[56:59], v[88:91]
	s_nop 3
	global_load_dwordx4 v[124:127], v249, s[16:17]
	s_cmp_lt_u32 s33, 28
	s_cselect_b32 s43, 0x200, 0
	s_add_u32 s16, s16, s43
	s_addc_u32 s17, s17, 0
	s_add_i32 s33, s33, 1
	s_nop 7
	s_nop 7
	v_cvt_pk_bf16_f32 v140, v60, v61
	v_cvt_pk_bf16_f32 v141, v62, v63
	ds_write_b64 v215, v[140:141] offset:12544
	v_cvt_pk_bf16_f32 v144, v64, v65
	v_cvt_pk_bf16_f32 v145, v66, v67
	ds_write_b64 v215, v[144:145] offset:16640
	s_nop 1
	v_cvt_pk_bf16_f32 v140, v68, v69
	v_cvt_pk_bf16_f32 v141, v70, v71
	ds_write_b64 v214, v[140:141] offset:12544
	v_cvt_pk_bf16_f32 v144, v72, v73
	v_cvt_pk_bf16_f32 v145, v74, v75
	ds_write_b64 v214, v[144:145] offset:16640
	s_nop 1
	v_cvt_pk_bf16_f32 v140, v76, v77
	v_cvt_pk_bf16_f32 v141, v78, v79
	ds_write_b64 v213, v[140:141] offset:12544
	v_cvt_pk_bf16_f32 v144, v80, v81
	v_cvt_pk_bf16_f32 v145, v82, v83
	ds_write_b64 v213, v[144:145] offset:16640
	s_nop 1
	v_cvt_pk_bf16_f32 v140, v84, v85
	v_cvt_pk_bf16_f32 v141, v86, v87
	ds_write_b64 v212, v[140:141] offset:12544
	v_cvt_pk_bf16_f32 v144, v88, v89
	v_cvt_pk_bf16_f32 v145, v90, v91
	ds_write_b64 v212, v[144:145] offset:16640
	s_nop 1
	s_waitcnt vmcnt(7)
	s_waitcnt lgkmcnt(0)
	s_barrier
	ds_read_b128 v[44:47], v217 offset:12288
	ds_read_b128 v[48:51], v217 offset:14336
	ds_read_b128 v[12:15], v227 offset:0
	ds_read_b128 v[16:19], v227 offset:2048
	ds_read_b128 v[20:23], v227 offset:4096
	ds_read_b128 v[24:27], v227 offset:6144
	ds_read_b128 v[52:55], v216 offset:12288
	ds_read_b128 v[56:59], v216 offset:14336
	ds_read_b128 v[28:31], v226 offset:0
	ds_read_b128 v[32:35], v226 offset:2048
	ds_read_b128 v[36:39], v226 offset:4096
	ds_read_b128 v[40:43], v226 offset:6144
	s_waitcnt vmcnt(12)
	v_mov_b32_dpp v96, v92 quad_perm:[0,0,0,0] row_mask:0xf bank_mask:0xf
	v_mov_b32_dpp v97, v93 quad_perm:[0,0,0,0] row_mask:0xf bank_mask:0xf
	v_mov_b32_dpp v98, v94 quad_perm:[0,0,0,0] row_mask:0xf bank_mask:0xf
	v_mov_b32_dpp v99, v95 quad_perm:[0,0,0,0] row_mask:0xf bank_mask:0xf
	v_mov_b32_dpp v100, v92 quad_perm:[1,1,1,1] row_mask:0xf bank_mask:0xf
	v_mov_b32_dpp v101, v93 quad_perm:[1,1,1,1] row_mask:0xf bank_mask:0xf
	v_mov_b32_dpp v102, v94 quad_perm:[1,1,1,1] row_mask:0xf bank_mask:0xf
	v_mov_b32_dpp v103, v95 quad_perm:[1,1,1,1] row_mask:0xf bank_mask:0xf
	v_mov_b32_dpp v104, v92 quad_perm:[2,2,2,2] row_mask:0xf bank_mask:0xf
	v_mov_b32_dpp v105, v93 quad_perm:[2,2,2,2] row_mask:0xf bank_mask:0xf
	v_mov_b32_dpp v106, v94 quad_perm:[2,2,2,2] row_mask:0xf bank_mask:0xf
	v_mov_b32_dpp v107, v95 quad_perm:[2,2,2,2] row_mask:0xf bank_mask:0xf
	v_mov_b32_dpp v112, v92 quad_perm:[3,3,3,3] row_mask:0xf bank_mask:0xf
	v_mov_b32_dpp v113, v93 quad_perm:[3,3,3,3] row_mask:0xf bank_mask:0xf
	v_mov_b32_dpp v114, v94 quad_perm:[3,3,3,3] row_mask:0xf bank_mask:0xf
	v_mov_b32_dpp v115, v95 quad_perm:[3,3,3,3] row_mask:0xf bank_mask:0xf
	v_pk_mul_f32 v[60:61], v[60:61], v[96:97]
	v_pk_mul_f32 v[62:63], v[62:63], v[98:99]
	v_pk_mul_f32 v[64:65], v[64:65], v[96:97]
	v_pk_mul_f32 v[66:67], v[66:67], v[98:99]
	v_pk_mul_f32 v[68:69], v[68:69], v[100:101]
	v_pk_mul_f32 v[70:71], v[70:71], v[102:103]
	v_pk_mul_f32 v[72:73], v[72:73], v[100:101]
	v_pk_mul_f32 v[74:75], v[74:75], v[102:103]
	v_pk_mul_f32 v[76:77], v[76:77], v[104:105]
	v_pk_mul_f32 v[78:79], v[78:79], v[106:107]
	v_pk_mul_f32 v[80:81], v[80:81], v[104:105]
	v_pk_mul_f32 v[82:83], v[82:83], v[106:107]
	v_pk_mul_f32 v[84:85], v[84:85], v[112:113]
	v_pk_mul_f32 v[86:87], v[86:87], v[114:115]
	v_pk_mul_f32 v[88:89], v[88:89], v[112:113]
	v_pk_mul_f32 v[90:91], v[90:91], v[114:115]
	s_add_i32 m0, s46, 0x14000
	s_nop 0
	global_load_lds_dwordx4 v255, s[8:9]
	s_add_i32 m0, s46, 0x14400
	s_nop 0
	global_load_lds_dwordx4 v254, s[8:9]
	s_add_i32 m0, s47, 0x14000
	s_nop 0
	global_load_lds_dwordx4 v253, s[10:11]
	s_add_i32 m0, s48, 0x14000
	s_nop 0
	global_load_lds_dwordx4 v252, s[12:13]
	s_add_i32 m0, s48, 0x14400
	s_nop 0
	global_load_lds_dwordx4 v251, s[12:13]
	s_cmp_lt_u32 s33, 29
	s_cselect_b32 s43, 0x10000, 0
	s_add_u32 s8, s8, s43
	s_addc_u32 s9, s9, 0
	s_cmp_lt_u32 s33, 29
	s_cselect_b32 s43, 0x2000, 0
	s_add_u32 s10, s10, s43
	s_addc_u32 s11, s11, 0
	s_cmp_lt_u32 s33, 29
	s_cselect_b32 s43, 0x4000, 0
	s_add_u32 s12, s12, s43
	s_addc_u32 s13, s13, 0
	s_waitcnt lgkmcnt(6)
	v_mfma_f32_16x16x32_bf16 v[60:63], v[12:15], v[44:47], v[60:63]
	v_mfma_f32_16x16x32_bf16 v[64:67], v[12:15], v[48:51], v[64:67]
	v_mfma_f32_16x16x32_bf16 v[68:71], v[16:19], v[44:47], v[68:71]
	v_mfma_f32_16x16x32_bf16 v[72:75], v[16:19], v[48:51], v[72:75]
	v_mfma_f32_16x16x32_bf16 v[76:79], v[20:23], v[44:47], v[76:79]
	v_mfma_f32_16x16x32_bf16 v[80:83], v[20:23], v[48:51], v[80:83]
	v_mfma_f32_16x16x32_bf16 v[84:87], v[24:27], v[44:47], v[84:87]
	v_mfma_f32_16x16x32_bf16 v[88:91], v[24:27], v[48:51], v[88:91]
	s_waitcnt lgkmcnt(0)
	v_mfma_f32_16x16x32_bf16 v[60:63], v[28:31], v[52:55], v[60:63]
	v_mfma_f32_16x16x32_bf16 v[64:67], v[28:31], v[56:59], v[64:67]
	v_mfma_f32_16x16x32_bf16 v[68:71], v[32:35], v[52:55], v[68:71]
	v_mfma_f32_16x16x32_bf16 v[72:75], v[32:35], v[56:59], v[72:75]
	v_mfma_f32_16x16x32_bf16 v[76:79], v[36:39], v[52:55], v[76:79]
	v_mfma_f32_16x16x32_bf16 v[80:83], v[36:39], v[56:59], v[80:83]
	v_mfma_f32_16x16x32_bf16 v[84:87], v[40:43], v[52:55], v[84:87]
	v_mfma_f32_16x16x32_bf16 v[88:91], v[40:43], v[56:59], v[88:91]
	s_nop 3
	global_load_dwordx4 v[92:95], v249, s[16:17]
	s_cmp_lt_u32 s33, 28
	s_cselect_b32 s43, 0x200, 0
	s_add_u32 s16, s16, s43
	s_addc_u32 s17, s17, 0
	s_add_i32 s33, s33, 1
	s_nop 7
	s_nop 7
	v_cvt_pk_bf16_f32 v140, v60, v61
	v_cvt_pk_bf16_f32 v141, v62, v63
	ds_write_b64 v215, v[140:141] offset:0
	v_cvt_pk_bf16_f32 v144, v64, v65
	v_cvt_pk_bf16_f32 v145, v66, v67
	ds_write_b64 v215, v[144:145] offset:4096
	s_nop 1
	v_cvt_pk_bf16_f32 v140, v68, v69
	v_cvt_pk_bf16_f32 v141, v70, v71
	ds_write_b64 v214, v[140:141] offset:0
	v_cvt_pk_bf16_f32 v144, v72, v73
	v_cvt_pk_bf16_f32 v145, v74, v75
	ds_write_b64 v214, v[144:145] offset:4096
	s_nop 1
	v_cvt_pk_bf16_f32 v140, v76, v77
	v_cvt_pk_bf16_f32 v141, v78, v79
	ds_write_b64 v213, v[140:141] offset:0
	v_cvt_pk_bf16_f32 v144, v80, v81
	v_cvt_pk_bf16_f32 v145, v82, v83
	ds_write_b64 v213, v[144:145] offset:4096
	s_nop 1
	v_cvt_pk_bf16_f32 v140, v84, v85
	v_cvt_pk_bf16_f32 v141, v86, v87
	ds_write_b64 v212, v[140:141] offset:0
	v_cvt_pk_bf16_f32 v144, v88, v89
	v_cvt_pk_bf16_f32 v145, v90, v91
	ds_write_b64 v212, v[144:145] offset:4096
	s_nop 1
	s_waitcnt vmcnt(7)
	s_waitcnt lgkmcnt(0)
	s_barrier
	ds_read_b128 v[44:47], v217 offset:0
	ds_read_b128 v[48:51], v217 offset:2048
	ds_read_b128 v[12:15], v227 offset:40960
	ds_read_b128 v[16:19], v227 offset:43008
	ds_read_b128 v[20:23], v227 offset:45056
	ds_read_b128 v[24:27], v227 offset:47104
	ds_read_b128 v[52:55], v216 offset:0
	ds_read_b128 v[56:59], v216 offset:2048
	ds_read_b128 v[28:31], v226 offset:40960
	ds_read_b128 v[32:35], v226 offset:43008
	ds_read_b128 v[36:39], v226 offset:45056
	ds_read_b128 v[40:43], v226 offset:47104
	s_waitcnt vmcnt(12)
	v_mov_b32_dpp v96, v108 quad_perm:[0,0,0,0] row_mask:0xf bank_mask:0xf
	v_mov_b32_dpp v97, v109 quad_perm:[0,0,0,0] row_mask:0xf bank_mask:0xf
	v_mov_b32_dpp v98, v110 quad_perm:[0,0,0,0] row_mask:0xf bank_mask:0xf
	v_mov_b32_dpp v99, v111 quad_perm:[0,0,0,0] row_mask:0xf bank_mask:0xf
	v_mov_b32_dpp v100, v108 quad_perm:[1,1,1,1] row_mask:0xf bank_mask:0xf
	v_mov_b32_dpp v101, v109 quad_perm:[1,1,1,1] row_mask:0xf bank_mask:0xf
	v_mov_b32_dpp v102, v110 quad_perm:[1,1,1,1] row_mask:0xf bank_mask:0xf
	v_mov_b32_dpp v103, v111 quad_perm:[1,1,1,1] row_mask:0xf bank_mask:0xf
	v_mov_b32_dpp v104, v108 quad_perm:[2,2,2,2] row_mask:0xf bank_mask:0xf
	v_mov_b32_dpp v105, v109 quad_perm:[2,2,2,2] row_mask:0xf bank_mask:0xf
	v_mov_b32_dpp v106, v110 quad_perm:[2,2,2,2] row_mask:0xf bank_mask:0xf
	v_mov_b32_dpp v107, v111 quad_perm:[2,2,2,2] row_mask:0xf bank_mask:0xf
	v_mov_b32_dpp v112, v108 quad_perm:[3,3,3,3] row_mask:0xf bank_mask:0xf
	v_mov_b32_dpp v113, v109 quad_perm:[3,3,3,3] row_mask:0xf bank_mask:0xf
	v_mov_b32_dpp v114, v110 quad_perm:[3,3,3,3] row_mask:0xf bank_mask:0xf
	v_mov_b32_dpp v115, v111 quad_perm:[3,3,3,3] row_mask:0xf bank_mask:0xf
	v_pk_mul_f32 v[60:61], v[60:61], v[96:97]
	v_pk_mul_f32 v[62:63], v[62:63], v[98:99]
	v_pk_mul_f32 v[64:65], v[64:65], v[96:97]
	v_pk_mul_f32 v[66:67], v[66:67], v[98:99]
	v_pk_mul_f32 v[68:69], v[68:69], v[100:101]
	v_pk_mul_f32 v[70:71], v[70:71], v[102:103]
	v_pk_mul_f32 v[72:73], v[72:73], v[100:101]
	v_pk_mul_f32 v[74:75], v[74:75], v[102:103]
	v_pk_mul_f32 v[76:77], v[76:77], v[104:105]
	v_pk_mul_f32 v[78:79], v[78:79], v[106:107]
	v_pk_mul_f32 v[80:81], v[80:81], v[104:105]
	v_pk_mul_f32 v[82:83], v[82:83], v[106:107]
	v_pk_mul_f32 v[84:85], v[84:85], v[112:113]
	v_pk_mul_f32 v[86:87], v[86:87], v[114:115]
	v_pk_mul_f32 v[88:89], v[88:89], v[112:113]
	v_pk_mul_f32 v[90:91], v[90:91], v[114:115]
	s_mov_b32 m0, s46
	s_nop 0
	global_load_lds_dwordx4 v255, s[8:9]
	s_add_i32 m0, s46, 0x400
	s_nop 0
	global_load_lds_dwordx4 v254, s[8:9]
	s_mov_b32 m0, s47
	s_nop 0
	global_load_lds_dwordx4 v253, s[10:11]
	s_mov_b32 m0, s48
	s_nop 0
	global_load_lds_dwordx4 v252, s[12:13]
	s_add_i32 m0, s48, 0x400
	s_nop 0
	global_load_lds_dwordx4 v251, s[12:13]
	s_cmp_lt_u32 s33, 29
	s_cselect_b32 s43, 0x10000, 0
	s_add_u32 s8, s8, s43
	s_addc_u32 s9, s9, 0
	s_cmp_lt_u32 s33, 29
	s_cselect_b32 s43, 0x2000, 0
	s_add_u32 s10, s10, s43
	s_addc_u32 s11, s11, 0
	s_cmp_lt_u32 s33, 29
	s_cselect_b32 s43, 0x4000, 0
	s_add_u32 s12, s12, s43
	s_addc_u32 s13, s13, 0
	s_waitcnt lgkmcnt(6)
	v_mfma_f32_16x16x32_bf16 v[60:63], v[12:15], v[44:47], v[60:63]
	v_mfma_f32_16x16x32_bf16 v[64:67], v[12:15], v[48:51], v[64:67]
	v_mfma_f32_16x16x32_bf16 v[68:71], v[16:19], v[44:47], v[68:71]
	v_mfma_f32_16x16x32_bf16 v[72:75], v[16:19], v[48:51], v[72:75]
	v_mfma_f32_16x16x32_bf16 v[76:79], v[20:23], v[44:47], v[76:79]
	v_mfma_f32_16x16x32_bf16 v[80:83], v[20:23], v[48:51], v[80:83]
	v_mfma_f32_16x16x32_bf16 v[84:87], v[24:27], v[44:47], v[84:87]
	v_mfma_f32_16x16x32_bf16 v[88:91], v[24:27], v[48:51], v[88:91]
	s_waitcnt lgkmcnt(0)
	v_mfma_f32_16x16x32_bf16 v[60:63], v[28:31], v[52:55], v[60:63]
	v_mfma_f32_16x16x32_bf16 v[64:67], v[28:31], v[56:59], v[64:67]
	v_mfma_f32_16x16x32_bf16 v[68:71], v[32:35], v[52:55], v[68:71]
	v_mfma_f32_16x16x32_bf16 v[72:75], v[32:35], v[56:59], v[72:75]
	v_mfma_f32_16x16x32_bf16 v[76:79], v[36:39], v[52:55], v[76:79]
	v_mfma_f32_16x16x32_bf16 v[80:83], v[36:39], v[56:59], v[80:83]
	v_mfma_f32_16x16x32_bf16 v[84:87], v[40:43], v[52:55], v[84:87]
	v_mfma_f32_16x16x32_bf16 v[88:91], v[40:43], v[56:59], v[88:91]
	s_nop 3
	global_load_dwordx4 v[108:111], v249, s[16:17]
	s_cmp_lt_u32 s33, 28
	s_cselect_b32 s43, 0x200, 0
	s_add_u32 s16, s16, s43
	s_addc_u32 s17, s17, 0
	s_add_i32 s33, s33, 1
	s_nop 7
	s_nop 7
	v_cvt_pk_bf16_f32 v140, v60, v61
	v_cvt_pk_bf16_f32 v141, v62, v63
	ds_write_b64 v215, v[140:141] offset:12544
	v_cvt_pk_bf16_f32 v144, v64, v65
	v_cvt_pk_bf16_f32 v145, v66, v67
	ds_write_b64 v215, v[144:145] offset:16640
	s_nop 1
	v_cvt_pk_bf16_f32 v140, v68, v69
	v_cvt_pk_bf16_f32 v141, v70, v71
	ds_write_b64 v214, v[140:141] offset:12544
	v_cvt_pk_bf16_f32 v144, v72, v73
	v_cvt_pk_bf16_f32 v145, v74, v75
	ds_write_b64 v214, v[144:145] offset:16640
	s_nop 1
	v_cvt_pk_bf16_f32 v140, v76, v77
	v_cvt_pk_bf16_f32 v141, v78, v79
	ds_write_b64 v213, v[140:141] offset:12544
	v_cvt_pk_bf16_f32 v144, v80, v81
	v_cvt_pk_bf16_f32 v145, v82, v83
	ds_write_b64 v213, v[144:145] offset:16640
	s_nop 1
	v_cvt_pk_bf16_f32 v140, v84, v85
	v_cvt_pk_bf16_f32 v141, v86, v87
	ds_write_b64 v212, v[140:141] offset:12544
	v_cvt_pk_bf16_f32 v144, v88, v89
	v_cvt_pk_bf16_f32 v145, v90, v91
	ds_write_b64 v212, v[144:145] offset:16640
	s_nop 1
	s_waitcnt vmcnt(7)
	s_waitcnt lgkmcnt(0)
	s_barrier
	ds_read_b128 v[44:47], v217 offset:12288
	ds_read_b128 v[48:51], v217 offset:14336
	ds_read_b128 v[12:15], v225 offset:0
	ds_read_b128 v[16:19], v225 offset:2048
	ds_read_b128 v[20:23], v225 offset:4096
	ds_read_b128 v[24:27], v225 offset:6144
	ds_read_b128 v[52:55], v216 offset:12288
	ds_read_b128 v[56:59], v216 offset:14336
	ds_read_b128 v[28:31], v224 offset:0
	ds_read_b128 v[32:35], v224 offset:2048
	ds_read_b128 v[36:39], v224 offset:4096
	ds_read_b128 v[40:43], v224 offset:6144
	s_waitcnt vmcnt(12)
	v_mov_b32_dpp v96, v124 quad_perm:[0,0,0,0] row_mask:0xf bank_mask:0xf
	v_mov_b32_dpp v97, v125 quad_perm:[0,0,0,0] row_mask:0xf bank_mask:0xf
	v_mov_b32_dpp v98, v126 quad_perm:[0,0,0,0] row_mask:0xf bank_mask:0xf
	v_mov_b32_dpp v99, v127 quad_perm:[0,0,0,0] row_mask:0xf bank_mask:0xf
	v_mov_b32_dpp v100, v124 quad_perm:[1,1,1,1] row_mask:0xf bank_mask:0xf
	v_mov_b32_dpp v101, v125 quad_perm:[1,1,1,1] row_mask:0xf bank_mask:0xf
	v_mov_b32_dpp v102, v126 quad_perm:[1,1,1,1] row_mask:0xf bank_mask:0xf
	v_mov_b32_dpp v103, v127 quad_perm:[1,1,1,1] row_mask:0xf bank_mask:0xf
	v_mov_b32_dpp v104, v124 quad_perm:[2,2,2,2] row_mask:0xf bank_mask:0xf
	v_mov_b32_dpp v105, v125 quad_perm:[2,2,2,2] row_mask:0xf bank_mask:0xf
	v_mov_b32_dpp v106, v126 quad_perm:[2,2,2,2] row_mask:0xf bank_mask:0xf
	v_mov_b32_dpp v107, v127 quad_perm:[2,2,2,2] row_mask:0xf bank_mask:0xf
	v_mov_b32_dpp v112, v124 quad_perm:[3,3,3,3] row_mask:0xf bank_mask:0xf
	v_mov_b32_dpp v113, v125 quad_perm:[3,3,3,3] row_mask:0xf bank_mask:0xf
	v_mov_b32_dpp v114, v126 quad_perm:[3,3,3,3] row_mask:0xf bank_mask:0xf
	v_mov_b32_dpp v115, v127 quad_perm:[3,3,3,3] row_mask:0xf bank_mask:0xf
	v_pk_mul_f32 v[60:61], v[60:61], v[96:97]
	v_pk_mul_f32 v[62:63], v[62:63], v[98:99]
	v_pk_mul_f32 v[64:65], v[64:65], v[96:97]
	v_pk_mul_f32 v[66:67], v[66:67], v[98:99]
	v_pk_mul_f32 v[68:69], v[68:69], v[100:101]
	v_pk_mul_f32 v[70:71], v[70:71], v[102:103]
	v_pk_mul_f32 v[72:73], v[72:73], v[100:101]
	v_pk_mul_f32 v[74:75], v[74:75], v[102:103]
	v_pk_mul_f32 v[76:77], v[76:77], v[104:105]
	v_pk_mul_f32 v[78:79], v[78:79], v[106:107]
	v_pk_mul_f32 v[80:81], v[80:81], v[104:105]
	v_pk_mul_f32 v[82:83], v[82:83], v[106:107]
	v_pk_mul_f32 v[84:85], v[84:85], v[112:113]
	v_pk_mul_f32 v[86:87], v[86:87], v[114:115]
	v_pk_mul_f32 v[88:89], v[88:89], v[112:113]
	v_pk_mul_f32 v[90:91], v[90:91], v[114:115]
	s_add_i32 m0, s46, 0xa000
	s_nop 0
	global_load_lds_dwordx4 v255, s[8:9]
	s_add_i32 m0, s46, 0xa400
	s_nop 0
	global_load_lds_dwordx4 v254, s[8:9]
	s_add_i32 m0, s47, 0xa000
	s_nop 0
	global_load_lds_dwordx4 v253, s[10:11]
	s_add_i32 m0, s48, 0xa000
	s_nop 0
	global_load_lds_dwordx4 v252, s[12:13]
	s_add_i32 m0, s48, 0xa400
	s_nop 0
	global_load_lds_dwordx4 v251, s[12:13]
	s_cmp_lt_u32 s33, 29
	s_cselect_b32 s43, 0x10000, 0
	s_add_u32 s8, s8, s43
	s_addc_u32 s9, s9, 0
	s_cmp_lt_u32 s33, 29
	s_cselect_b32 s43, 0x2000, 0
	s_add_u32 s10, s10, s43
	s_addc_u32 s11, s11, 0
	s_cmp_lt_u32 s33, 29
	s_cselect_b32 s43, 0x4000, 0
	s_add_u32 s12, s12, s43
	s_addc_u32 s13, s13, 0
	s_waitcnt lgkmcnt(6)
	v_mfma_f32_16x16x32_bf16 v[60:63], v[12:15], v[44:47], v[60:63]
	v_mfma_f32_16x16x32_bf16 v[64:67], v[12:15], v[48:51], v[64:67]
	v_mfma_f32_16x16x32_bf16 v[68:71], v[16:19], v[44:47], v[68:71]
	v_mfma_f32_16x16x32_bf16 v[72:75], v[16:19], v[48:51], v[72:75]
	v_mfma_f32_16x16x32_bf16 v[76:79], v[20:23], v[44:47], v[76:79]
	v_mfma_f32_16x16x32_bf16 v[80:83], v[20:23], v[48:51], v[80:83]
	v_mfma_f32_16x16x32_bf16 v[84:87], v[24:27], v[44:47], v[84:87]
	v_mfma_f32_16x16x32_bf16 v[88:91], v[24:27], v[48:51], v[88:91]
	s_waitcnt lgkmcnt(0)
	v_mfma_f32_16x16x32_bf16 v[60:63], v[28:31], v[52:55], v[60:63]
	v_mfma_f32_16x16x32_bf16 v[64:67], v[28:31], v[56:59], v[64:67]
	v_mfma_f32_16x16x32_bf16 v[68:71], v[32:35], v[52:55], v[68:71]
	v_mfma_f32_16x16x32_bf16 v[72:75], v[32:35], v[56:59], v[72:75]
	v_mfma_f32_16x16x32_bf16 v[76:79], v[36:39], v[52:55], v[76:79]
	v_mfma_f32_16x16x32_bf16 v[80:83], v[36:39], v[56:59], v[80:83]
	v_mfma_f32_16x16x32_bf16 v[84:87], v[40:43], v[52:55], v[84:87]
	v_mfma_f32_16x16x32_bf16 v[88:91], v[40:43], v[56:59], v[88:91]
	s_nop 3
	global_load_dwordx4 v[124:127], v249, s[16:17]
	s_cmp_lt_u32 s33, 28
	s_cselect_b32 s43, 0x200, 0
	s_add_u32 s16, s16, s43
	s_addc_u32 s17, s17, 0
	s_add_i32 s33, s33, 1
	s_nop 7
	s_nop 7
	v_cvt_pk_bf16_f32 v140, v60, v61
	v_cvt_pk_bf16_f32 v141, v62, v63
	ds_write_b64 v215, v[140:141] offset:0
	v_cvt_pk_bf16_f32 v144, v64, v65
	v_cvt_pk_bf16_f32 v145, v66, v67
	ds_write_b64 v215, v[144:145] offset:4096
	s_nop 1
	v_cvt_pk_bf16_f32 v140, v68, v69
	v_cvt_pk_bf16_f32 v141, v70, v71
	ds_write_b64 v214, v[140:141] offset:0
	v_cvt_pk_bf16_f32 v144, v72, v73
	v_cvt_pk_bf16_f32 v145, v74, v75
	ds_write_b64 v214, v[144:145] offset:4096
	s_nop 1
	v_cvt_pk_bf16_f32 v140, v76, v77
	v_cvt_pk_bf16_f32 v141, v78, v79
	ds_write_b64 v213, v[140:141] offset:0
	v_cvt_pk_bf16_f32 v144, v80, v81
	v_cvt_pk_bf16_f32 v145, v82, v83
	ds_write_b64 v213, v[144:145] offset:4096
	s_nop 1
	v_cvt_pk_bf16_f32 v140, v84, v85
	v_cvt_pk_bf16_f32 v141, v86, v87
	ds_write_b64 v212, v[140:141] offset:0
	v_cvt_pk_bf16_f32 v144, v88, v89
	v_cvt_pk_bf16_f32 v145, v90, v91
	ds_write_b64 v212, v[144:145] offset:4096
	s_nop 1
	s_waitcnt vmcnt(7)
	s_waitcnt lgkmcnt(0)
	s_barrier
	s_branch .Lp3S_loop
; __device__ __forceinline__ void gla_scan_item(const Ctx& C, int item, LAS unsigned char* lds, int tid) {
;     ...
;     float* So = C.out + OUT_GLAP + ((size_t)bh * 128 + wave * 16 + quad * 4) * 256 + sl * 32 + l15;
; #pragma unroll
;     for (int v2 = 0; v2 < 2; ++v2)
; #pragma unroll
;         for (int j = 0; j < 4; ++j) So[(size_t)j * 256 + v2 * 16] = S[v2][j];
;     __syncthreads();
.Lp3S_tail:
	s_nop 7
	global_store_dword v245, v60, s[34:35] offset:0
	global_store_dword v245, v61, s[34:35] offset:1024
	global_store_dword v245, v62, s[34:35] offset:2048
	global_store_dword v245, v63, s[34:35] offset:3072
	global_store_dword v245, v64, s[34:35] offset:64
	global_store_dword v245, v65, s[34:35] offset:1088
	global_store_dword v245, v66, s[34:35] offset:2112
	global_store_dword v245, v67, s[34:35] offset:3136
	global_store_dword v244, v68, s[34:35] offset:0
	global_store_dword v244, v69, s[34:35] offset:1024
	global_store_dword v244, v70, s[34:35] offset:2048
	global_store_dword v244, v71, s[34:35] offset:3072
	global_store_dword v244, v72, s[34:35] offset:64
	global_store_dword v244, v73, s[34:35] offset:1088
	global_store_dword v244, v74, s[34:35] offset:2112
	global_store_dword v244, v75, s[34:35] offset:3136
	global_store_dword v243, v76, s[34:35] offset:0
	global_store_dword v243, v77, s[34:35] offset:1024
	global_store_dword v243, v78, s[34:35] offset:2048
	global_store_dword v243, v79, s[34:35] offset:3072
	global_store_dword v243, v80, s[34:35] offset:64
	global_store_dword v243, v81, s[34:35] offset:1088
	global_store_dword v243, v82, s[34:35] offset:2112
	global_store_dword v243, v83, s[34:35] offset:3136
	global_store_dword v242, v84, s[34:35] offset:0
	global_store_dword v242, v85, s[34:35] offset:1024
	global_store_dword v242, v86, s[34:35] offset:2048
	global_store_dword v242, v87, s[34:35] offset:3072
	global_store_dword v242, v88, s[34:35] offset:64
	global_store_dword v242, v89, s[34:35] offset:1088
	global_store_dword v242, v90, s[34:35] offset:2112
	global_store_dword v242, v91, s[34:35] offset:3136
	s_waitcnt vmcnt(0) lgkmcnt(0)
	s_barrier
	s_add_i32 s3, s3, s42
	s_cmpk_lt_i32 s3, 0x100
	s_cbranch_scc1 .Lp3S_item
	s_branch .Lp3_done

.Lp3V_loop:
	s_waitcnt vmcnt(6)
	ds_write_b16 v211, v16 offset:12288
	ds_write_b16_d16_hi v210, v16 offset:12288
	ds_write_b16 v209, v17 offset:12288
	ds_write_b16_d16_hi v208, v17 offset:12288
	ds_write_b16 v207, v18 offset:12288
	ds_write_b16_d16_hi v206, v18 offset:12288
	ds_write_b16 v205, v19 offset:12288
	ds_write_b16_d16_hi v204, v19 offset:12288
	s_add_i32 m0, s46, 0x14000
	s_nop 0
	global_load_lds_dwordx4 v255, s[8:9]
	s_add_i32 m0, s46, 0x14400
	s_nop 0
	global_load_lds_dwordx4 v254, s[8:9]
	s_add_i32 m0, s47, 0x14000
	s_nop 0
	global_load_lds_dwordx4 v253, s[10:11]
	s_add_i32 m0, s48, 0x14000
	s_nop 0
	global_load_lds_dwordx4 v252, s[12:13]
	s_add_i32 m0, s48, 0x14400
	s_nop 0
	global_load_lds_dwordx4 v251, s[12:13]
	s_cmp_lt_u32 s33, 29
	s_cselect_b32 s43, 0x10000, 0
	s_add_u32 s8, s8, s43
	s_addc_u32 s9, s9, 0
	s_cmp_lt_u32 s33, 29
	s_cselect_b32 s43, 0x2000, 0
	s_add_u32 s10, s10, s43
	s_addc_u32 s11, s11, 0
	s_cmp_lt_u32 s33, 29
	s_cselect_b32 s43, 0x4000, 0
	s_add_u32 s12, s12, s43
	s_addc_u32 s13, s13, 0
	global_load_dwordx4 v[12:15], v250, s[14:15]
	s_cmp_lt_u32 s33, 28
	s_cselect_b32 s43, 0x100000, 0
	s_add_u32 s14, s14, s43
	s_addc_u32 s15, s15, 0
	s_add_i32 s33, s33, 1
	s_waitcnt vmcnt(7)
	s_waitcnt lgkmcnt(0)
	s_barrier
	s_waitcnt vmcnt(6)
	ds_write_b16 v211, v20 offset:0
	ds_write_b16_d16_hi v210, v20 offset:0
	ds_write_b16 v209, v21 offset:0
	ds_write_b16_d16_hi v208, v21 offset:0
	ds_write_b16 v207, v22 offset:0
	ds_write_b16_d16_hi v206, v22 offset:0
	ds_write_b16 v205, v23 offset:0
	ds_write_b16_d16_hi v204, v23 offset:0
	s_mov_b32 m0, s46
	s_nop 0
	global_load_lds_dwordx4 v255, s[8:9]
	s_add_i32 m0, s46, 0x400
	s_nop 0
	global_load_lds_dwordx4 v254, s[8:9]
	s_mov_b32 m0, s47
	s_nop 0
	global_load_lds_dwordx4 v253, s[10:11]
	s_mov_b32 m0, s48
	s_nop 0
	global_load_lds_dwordx4 v252, s[12:13]
	s_add_i32 m0, s48, 0x400
	s_nop 0
	global_load_lds_dwordx4 v251, s[12:13]
	s_cmp_lt_u32 s33, 29
	s_cselect_b32 s43, 0x10000, 0
	s_add_u32 s8, s8, s43
	s_addc_u32 s9, s9, 0
	s_cmp_lt_u32 s33, 29
	s_cselect_b32 s43, 0x2000, 0
	s_add_u32 s10, s10, s43
	s_addc_u32 s11, s11, 0
	s_cmp_lt_u32 s33, 29
	s_cselect_b32 s43, 0x4000, 0
	s_add_u32 s12, s12, s43
	s_addc_u32 s13, s13, 0
	global_load_dwordx4 v[16:19], v250, s[14:15]
	s_cmp_lt_u32 s33, 28
	s_cselect_b32 s43, 0x100000, 0
	s_add_u32 s14, s14, s43
	s_addc_u32 s15, s15, 0
	s_add_i32 s33, s33, 1
	s_waitcnt vmcnt(7)
	s_waitcnt lgkmcnt(0)
	s_barrier
	s_cmp_gt_u32 s33, 31
	s_cbranch_scc1 .Lp3V_tail
	s_waitcnt vmcnt(6)
	ds_write_b16 v211, v12 offset:12288
	ds_write_b16_d16_hi v210, v12 offset:12288
	ds_write_b16 v209, v13 offset:12288
	ds_write_b16_d16_hi v208, v13 offset:12288
	ds_write_b16 v207, v14 offset:12288
	ds_write_b16_d16_hi v206, v14 offset:12288
	ds_write_b16 v205, v15 offset:12288
	ds_write_b16_d16_hi v204, v15 offset:12288
	s_add_i32 m0, s46, 0xa000
	s_nop 0
	global_load_lds_dwordx4 v255, s[8:9]
	s_add_i32 m0, s46, 0xa400
	s_nop 0
	global_load_lds_dwordx4 v254, s[8:9]
	s_add_i32 m0, s47, 0xa000
	s_nop 0
	global_load_lds_dwordx4 v253, s[10:11]
	s_add_i32 m0, s48, 0xa000
	s_nop 0
	global_load_lds_dwordx4 v252, s[12:13]
	s_add_i32 m0, s48, 0xa400
	s_nop 0
	global_load_lds_dwordx4 v251, s[12:13]
	s_cmp_lt_u32 s33, 29
	s_cselect_b32 s43, 0x10000, 0
	s_add_u32 s8, s8, s43
	s_addc_u32 s9, s9, 0
	s_cmp_lt_u32 s33, 29
	s_cselect_b32 s43, 0x2000, 0
	s_add_u32 s10, s10, s43
	s_addc_u32 s11, s11, 0
	s_cmp_lt_u32 s33, 29
	s_cselect_b32 s43, 0x4000, 0
	s_add_u32 s12, s12, s43
	s_addc_u32 s13, s13, 0
	global_load_dwordx4 v[20:23], v250, s[14:15]
	s_cmp_lt_u32 s33, 28
	s_cselect_b32 s43, 0x100000, 0
	s_add_u32 s14, s14, s43
	s_addc_u32 s15, s15, 0
	s_add_i32 s33, s33, 1
	s_waitcnt vmcnt(7)
	s_waitcnt lgkmcnt(0)
	s_barrier
	s_waitcnt vmcnt(6)
	ds_write_b16 v211, v16 offset:0
	ds_write_b16_d16_hi v210, v16 offset:0
	ds_write_b16 v209, v17 offset:0
	ds_write_b16_d16_hi v208, v17 offset:0
	ds_write_b16 v207, v18 offset:0
	ds_write_b16_d16_hi v206, v18 offset:0
	ds_write_b16 v205, v19 offset:0
	ds_write_b16_d16_hi v204, v19 offset:0
	s_add_i32 m0, s46, 0x14000
	s_nop 0
	global_load_lds_dwordx4 v255, s[8:9]
	s_add_i32 m0, s46, 0x14400
	s_nop 0
	global_load_lds_dwordx4 v254, s[8:9]
	s_add_i32 m0, s47, 0x14000
	s_nop 0
	global_load_lds_dwordx4 v253, s[10:11]
	s_add_i32 m0, s48, 0x14000
	s_nop 0
	global_load_lds_dwordx4 v252, s[12:13]
	s_add_i32 m0, s48, 0x14400
	s_nop 0
	global_load_lds_dwordx4 v251, s[12:13]
	s_cmp_lt_u32 s33, 29
	s_cselect_b32 s43, 0x10000, 0
	s_add_u32 s8, s8, s43
	s_addc_u32 s9, s9, 0
	s_cmp_lt_u32 s33, 29
	s_cselect_b32 s43, 0x2000, 0
	s_add_u32 s10, s10, s43
	s_addc_u32 s11, s11, 0
	s_cmp_lt_u32 s33, 29
	s_cselect_b32 s43, 0x4000, 0
	s_add_u32 s12, s12, s43
	s_addc_u32 s13, s13, 0
	global_load_dwordx4 v[12:15], v250, s[14:15]
	s_cmp_lt_u32 s33, 28
	s_cselect_b32 s43, 0x100000, 0
	s_add_u32 s14, s14, s43
	s_addc_u32 s15, s15, 0
	s_add_i32 s33, s33, 1
	s_waitcnt vmcnt(7)
	s_waitcnt lgkmcnt(0)
	s_barrier
	s_waitcnt vmcnt(6)
	ds_write_b16 v211, v20 offset:12288
	ds_write_b16_d16_hi v210, v20 offset:12288
	ds_write_b16 v209, v21 offset:12288
	ds_write_b16_d16_hi v208, v21 offset:12288
	ds_write_b16 v207, v22 offset:12288
	ds_write_b16_d16_hi v206, v22 offset:12288
	ds_write_b16 v205, v23 offset:12288
	ds_write_b16_d16_hi v204, v23 offset:12288
	s_mov_b32 m0, s46
	s_nop 0
	global_load_lds_dwordx4 v255, s[8:9]
	s_add_i32 m0, s46, 0x400
	s_nop 0
	global_load_lds_dwordx4 v254, s[8:9]
	s_mov_b32 m0, s47
	s_nop 0
	global_load_lds_dwordx4 v253, s[10:11]
	s_mov_b32 m0, s48
	s_nop 0
	global_load_lds_dwordx4 v252, s[12:13]
	s_add_i32 m0, s48, 0x400
	s_nop 0
	global_load_lds_dwordx4 v251, s[12:13]
	s_cmp_lt_u32 s33, 29
	s_cselect_b32 s43, 0x10000, 0
	s_add_u32 s8, s8, s43
	s_addc_u32 s9, s9, 0
	s_cmp_lt_u32 s33, 29
	s_cselect_b32 s43, 0x2000, 0
	s_add_u32 s10, s10, s43
	s_addc_u32 s11, s11, 0
	s_cmp_lt_u32 s33, 29
	s_cselect_b32 s43, 0x4000, 0
	s_add_u32 s12, s12, s43
	s_addc_u32 s13, s13, 0
	global_load_dwordx4 v[16:19], v250, s[14:15]
	s_cmp_lt_u32 s33, 28
	s_cselect_b32 s43, 0x100000, 0
	s_add_u32 s14, s14, s43
	s_addc_u32 s15, s15, 0
	s_add_i32 s33, s33, 1
	s_waitcnt vmcnt(7)
	s_waitcnt lgkmcnt(0)
	s_barrier
	s_waitcnt vmcnt(6)
	ds_write_b16 v211, v12 offset:0
	ds_write_b16_d16_hi v210, v12 offset:0
	ds_write_b16 v209, v13 offset:0
	ds_write_b16_d16_hi v208, v13 offset:0
	ds_write_b16 v207, v14 offset:0
	ds_write_b16_d16_hi v206, v14 offset:0
	ds_write_b16 v205, v15 offset:0
	ds_write_b16_d16_hi v204, v15 offset:0
	s_add_i32 m0, s46, 0xa000
	s_nop 0
	global_load_lds_dwordx4 v255, s[8:9]
	s_add_i32 m0, s46, 0xa400
	s_nop 0
	global_load_lds_dwordx4 v254, s[8:9]
	s_add_i32 m0, s47, 0xa000
	s_nop 0
	global_load_lds_dwordx4 v253, s[10:11]
	s_add_i32 m0, s48, 0xa000
	s_nop 0
	global_load_lds_dwordx4 v252, s[12:13]
	s_add_i32 m0, s48, 0xa400
	s_nop 0
	global_load_lds_dwordx4 v251, s[12:13]
	s_cmp_lt_u32 s33, 29
	s_cselect_b32 s43, 0x10000, 0
	s_add_u32 s8, s8, s43
	s_addc_u32 s9, s9, 0
	s_cmp_lt_u32 s33, 29
	s_cselect_b32 s43, 0x2000, 0
	s_add_u32 s10, s10, s43
	s_addc_u32 s11, s11, 0
	s_cmp_lt_u32 s33, 29
	s_cselect_b32 s43, 0x4000, 0
	s_add_u32 s12, s12, s43
	s_addc_u32 s13, s13, 0
	global_load_dwordx4 v[20:23], v250, s[14:15]
	s_cmp_lt_u32 s33, 28
	s_cselect_b32 s43, 0x100000, 0
	s_add_u32 s14, s14, s43
	s_addc_u32 s15, s15, 0
	s_add_i32 s33, s33, 1
	s_waitcnt vmcnt(7)
	s_waitcnt lgkmcnt(0)
	s_barrier
	s_branch .Lp3V_loop
